# boundary-block tile loads: position clamp as one v_med3_i32 instead of v_max_i32 + v_min_i32 (75 sites, on the critical workgroups of the attention phase); otherwise v65
# speedup vs baseline: 1.0022x; 1.0022x over previous
; template <bool EDGE>
; __device__ __forceinline__ void tile_load(TileLd& L, const bf16_t* kp, const bf16_t* vp, int S, int pos0, int dil, int k0, int lane) {
;     asm volatile("" : "+s"(k0), "+s"(pos0));
;     const int i16 = lane & 15, quad = lane >> 4;
; #pragma unroll
;     for (int st = 0; st < 2; ++st) { int pos = pos0 + dil * (k0 + 16 * st + i16); if (EDGE) pos = min(max(pos, 0), S - 1);
;         const bf16_t* p = kp + (long)pos * NIN + quad * 8; L.k[st][0] = *(const bf16x8*)p; L.k[st][1] = *(const bf16x8*)(p + 32); }
; #pragma unroll
;     for (int i = 0; i < 4; ++i) { int pos = pos0 + dil * (k0 + 8 * i + (lane >> 3)); if (EDGE) pos = min(max(pos, 0), S - 1);
;         L.v[i] = *(const u32x4*)(vp + (long)pos * NIN + (lane & 7) * 8); }
; }
; __device__ __forceinline__ void mixer_a2(Frame& F, const Trunk& T) {
;     ...
;             bf16x8 q[2][2]; f32x4 o[2][4]; float m[2], l[2];
; #pragma unroll
;             for (int g = 0; g < 2; ++g) { const bf16_t* qp = proj + (rowb + pos0 + 16 * g + i16) * NIN + C_QA + h * 64 + quad * 8; q[g][0] = *(const bf16x8*)qp; q[g][1] = *(const bf16x8*)(qp + 32);
;                 o[g][0] = z4; o[g][1] = z4; o[g][2] = z4; o[g][3] = z4; m[g] = -1e20f; l[g] = 0.f; }
;             if (pos0 >= 64 && pos0 + 96 <= T.S) a2_pass1<false>(kp, vp, T.S, pos0, lut, vimg, lane, q, o, m, l);
.LBB0_500:
	s_and_b64 vcc, exec, s[0:1]
	s_cbranch_vccz .LBB0_522
	s_mov_b32 s0, s8
	s_movk_i32 s1, 0xffc0
	s_add_i32 s7, s0, s1
	v_add_u32_e32 v18, s7, v199
	v_med3_i32 v16, v18, 0, s70
	v_mad_u64_u32 v[16:17], s[0:1], v16, s97, v[186:187]
	global_load_dwordx4 v[28:31], v[16:17], off offset:1536
	global_load_dwordx4 v[24:27], v[16:17], off offset:1600
	v_add_u32_e32 v16, 16, v18
	v_lshlrev_b32_e32 v32, 1, v201
	v_mov_b32_e32 v33, v157
	v_add_u32_e32 v36, s7, v200
	v_lshl_add_u64 v[118:119], s[92:93], 0, v[32:33]
	v_add_u32_e32 v34, 8, v36
	v_med3_i32 v16, v16, 0, s70
	v_med3_i32 v32, v36, 0, s70
	v_mad_u64_u32 v[16:17], s[0:1], v16, s97, v[186:187]
	v_mad_u64_u32 v[32:33], s[0:1], v32, s97, v[118:119]
	v_med3_i32 v34, v34, 0, s70
	global_load_dwordx4 v[20:23], v[16:17], off offset:1536
	s_nop 0
	global_load_dwordx4 v[16:19], v[16:17], off offset:1600
	v_mad_u64_u32 v[34:35], s[0:1], v34, s97, v[118:119]
	global_load_dwordx4 v[80:83], v[32:33], off offset:3072
	global_load_dwordx4 v[84:87], v[34:35], off offset:3072
	v_add_u32_e32 v32, 16, v36
	v_add_u32_e32 v34, 24, v36
	v_med3_i32 v32, v32, 0, s70
	v_mad_u64_u32 v[32:33], s[0:1], v32, s97, v[118:119]
	v_med3_i32 v34, v34, 0, s70
	v_mad_u64_u32 v[34:35], s[0:1], v34, s97, v[118:119]
	global_load_dwordx4 v[88:91], v[32:33], off offset:3072
	global_load_dwordx4 v[92:95], v[34:35], off offset:3072
	v_mov_b32_e32 v34, v157
	v_mov_b32_e32 v35, v157
	v_mov_b32_e32 v161, v160
	v_mov_b32_e32 v32, v157
	v_mov_b32_e32 v33, v157
	v_mov_b64_e32 v[38:39], v[34:35]
	v_mov_b64_e32 v[42:43], v[34:35]
	v_mov_b64_e32 v[46:47], v[34:35]
	v_mov_b64_e32 v[66:67], v[34:35]
	v_mov_b64_e32 v[70:71], v[34:35]
	v_mov_b64_e32 v[74:75], v[34:35]
	v_mov_b64_e32 v[78:79], v[34:35]
	s_mov_b32 s7, 0
	v_mov_b32_e32 v114, v157
	v_mov_b32_e32 v115, v157
	s_mov_b64 s[24:25], -1
	v_mov_b64_e32 v[36:37], v[32:33]
	v_mov_b64_e32 v[40:41], v[32:33]
	v_mov_b64_e32 v[44:45], v[32:33]
	v_mov_b64_e32 v[64:65], v[32:33]
	v_mov_b64_e32 v[68:69], v[32:33]
	v_mov_b64_e32 v[72:73], v[32:33]
	v_mov_b64_e32 v[76:77], v[32:33]
	v_mov_b64_e32 v[116:117], v[160:161]
	s_branch .LBB0_504

; __device__ __forceinline__ float shx(float v, int mask, int lane) { return __builtin_bit_cast(float, __builtin_amdgcn_ds_bpermute((lane ^ mask) << 2, __builtin_bit_cast(int, v))); }
; #define LAS __attribute__((address_space(3)))
; __device__ __forceinline__ float ex2(float x) { return __builtin_amdgcn_exp2f(x); }
; #define MFMA16(a, b, c) __builtin_amdgcn_mfma_f32_16x16x32_bf16(a, b, c, 0, 0, 0)
; template <bool EDGE>
; __device__ __forceinline__ void tile_load(TileLd& L, const bf16_t* kp, const bf16_t* vp, int S, int pos0, int dil, int k0, int lane) {
;     asm volatile("" : "+s"(k0), "+s"(pos0));
;     const int i16 = lane & 15, quad = lane >> 4;
; #pragma unroll
;     for (int st = 0; st < 2; ++st) { int pos = pos0 + dil * (k0 + 16 * st + i16); if (EDGE) pos = min(max(pos, 0), S - 1);
;         const bf16_t* p = kp + (long)pos * NIN + quad * 8; L.k[st][0] = *(const bf16x8*)p; L.k[st][1] = *(const bf16x8*)(p + 32); }
; #pragma unroll
;     for (int i = 0; i < 4; ++i) { int pos = pos0 + dil * (k0 + 8 * i + (lane >> 3)); if (EDGE) pos = min(max(pos, 0), S - 1);
;         L.v[i] = *(const u32x4*)(vp + (long)pos * NIN + (lane & 7) * 8); }
; }
; template <int G, bool EDGE> ...
;     asm volatile("" : "+s"(k0));
;     const int quad = lane >> 4; const f32x4 z4 = {0.f, 0.f, 0.f, 0.f};
;     bf16x8 vf[4]; stage_v_regs(L.v, vimg, lane, vf);
;     constexpr float C2 = 0.125f * LOG2E, THR = 6.0f;
;     const int kb = k0 + 4 * quad;
; #pragma unroll
;     for (int g = 0; g < G; ++g) {
;         const LAS float* lutb = lut + (kb - ua[g] + R);
;         float sc[8]; float mx = -1e30f;
; #pragma unroll
;         for (int st = 0; st < 2; ++st) { f32x4 s = MFMA16(L.k[st][0], q[g][0], z4); s = MFMA16(L.k[st][1], q[g][1], s);
; #pragma unroll
;             for (int jj = 0; jj < 4; ++jj) { const int c = 16 * st + jj; const bool v = (unsigned)(kb - klo[g] + c) <= (unsigned)kspan[g];
;                 float x = s[jj] * C2 + lutb[g * lutstride + c]; x = v ? x : -1e30f; sc[4 * st + jj] = x; mx = fmaxf(mx, x); } }
;         if (__any(mx - m[g] > THR)) {
;             mx = fmaxf(mx, shx(mx, 16, lane)); mx = fmaxf(mx, shx(mx, 32, lane));
;             const float mn = fmaxf(m[g], mx), al = ex2(m[g] - mn); m[g] = mn; l[g] *= al;
; #pragma unroll
;             for (int nn = 0; nn < 4; ++nn) o[g][nn] = o[g][nn] * al;
;         }
.LBB0_504:
	s_sub_i32 s0, s7, 32
	s_mov_b32 s1, s0
	s_mov_b32 s34, s8
	s_add_i32 s1, s34, s1
	v_add_u32_e32 v50, s1, v199
	v_med3_i32 v48, v50, 0, s70
	v_mad_u64_u32 v[48:49], s[34:35], v48, s97, v[186:187]
	v_add_u32_e32 v108, s1, v200
	global_load_dwordx4 v[60:63], v[48:49], off offset:1536
	global_load_dwordx4 v[56:59], v[48:49], off offset:1600
	v_add_u32_e32 v48, 16, v50
	v_max_i32_e32 v96, 0, v108
	v_add_u32_e32 v100, 8, v108
	v_add_u32_e32 v104, 16, v108
	v_add_u32_e32 v108, 24, v108
	v_med3_i32 v48, v48, 0, s70
	v_min_i32_e32 v96, s70, v96
	v_med3_i32 v100, v100, 0, s70
	v_med3_i32 v104, v104, 0, s70
	v_med3_i32 v108, v108, 0, s70
	v_mad_u64_u32 v[52:53], s[34:35], v48, s97, v[186:187]
	v_mad_u64_u32 v[96:97], s[34:35], v96, s97, v[118:119]
	v_mad_u64_u32 v[100:101], s[34:35], v100, s97, v[118:119]
	v_mad_u64_u32 v[104:105], s[34:35], v104, s97, v[118:119]
	v_mad_u64_u32 v[108:109], s[34:35], v108, s97, v[118:119]
	global_load_dwordx4 v[48:51], v[52:53], off offset:1536
	s_nop 0
	global_load_dwordx4 v[52:55], v[52:53], off offset:1600
	s_sub_i32 s1, s7, 64
	global_load_dwordx4 v[96:99], v[96:97], off offset:3072
	v_add_u32_e32 v122, v210, v203
	global_load_dwordx4 v[100:103], v[100:101], off offset:3072
	s_waitcnt vmcnt(13)
	v_mfma_f32_16x16x32_bf16 v[128:131], v[28:31], v[8:11], 0
	global_load_dwordx4 v[104:107], v[104:105], off offset:3072
	s_nop 0
	global_load_dwordx4 v[108:111], v[108:109], off offset:3072
	s_waitcnt vmcnt(11)
	ds_write_b128 v122, v[80:83]
	s_waitcnt vmcnt(10)
	ds_write_b128 v122, v[84:87] offset:1152
	s_waitcnt vmcnt(9)
	ds_write_b128 v122, v[88:91] offset:2304
	s_waitcnt vmcnt(8)
	ds_write_b128 v122, v[92:95] offset:3456
	v_add_u32_e32 v126, s1, v204
	v_sub_u32_e32 v120, v126, v199
	v_lshl_add_u32 v125, v120, 2, s31
	ds_read_b64_tr_b16 v[92:93], v211
	ds_read_b64_tr_b16 v[80:81], v211 offset:32
	ds_read_b64_tr_b16 v[94:95], v211 offset:2304
	ds_read_b64_tr_b16 v[82:83], v211 offset:2336
	ds_read_b64_tr_b16 v[84:85], v211 offset:64
	ds_read_b64_tr_b16 v[86:87], v211 offset:2368
	ds_read_b64_tr_b16 v[88:89], v211 offset:96
	ds_read_b64_tr_b16 v[90:91], v211 offset:2400
	v_add_u32_e32 v123, 0x1300, v125
	ds_read2_b32 v[120:121], v123 offset1:1
	v_mfma_f32_16x16x32_bf16 v[128:131], v[24:27], v[12:15], v[128:131]
	v_sub_u32_e32 v136, v126, v214
	v_cmp_le_u32_e32 vcc, v136, v216
	v_add_u32_e32 v124, 0x1308, v125
	s_waitcnt lgkmcnt(0)
	s_nop 3
	v_fmamk_f32 v120, v128, 0x3e38aa3b, v120
	v_cndmask_b32_e32 v128, v235, v120, vcc
	v_add_u32_e32 v120, 1, v136
	v_fmac_f32_e32 v121, 0x3e38aa3b, v129
	v_cmp_le_u32_e32 vcc, v120, v216
	v_add_u32_e32 v129, 2, v136
	s_nop 0
	v_cndmask_b32_e32 v127, v235, v121, vcc
	ds_read2_b32 v[120:121], v124 offset1:1
	v_cmp_le_u32_e32 vcc, v129, v216
	v_max3_f32 v132, v128, s95, v127
	s_waitcnt lgkmcnt(0)
	v_fmamk_f32 v120, v130, 0x3e38aa3b, v120
	v_cndmask_b32_e32 v130, v235, v120, vcc
	v_add_u32_e32 v120, 3, v136
	v_fmac_f32_e32 v121, 0x3e38aa3b, v131
	v_cmp_le_u32_e32 vcc, v120, v216
	v_add_u32_e32 v120, 0x1340, v125
	v_add_u32_e32 v131, 16, v136
	v_cndmask_b32_e32 v129, v235, v121, vcc
	v_max3_f32 v137, v132, v130, v129
	v_mfma_f32_16x16x32_bf16 v[132:135], v[20:23], v[8:11], 0
	ds_read2_b32 v[120:121], v120 offset1:1
	v_cmp_le_u32_e32 vcc, v131, v216
	v_mfma_f32_16x16x32_bf16 v[132:135], v[16:19], v[12:15], v[132:135]
	s_waitcnt lgkmcnt(0)
	s_nop 6
	v_fmamk_f32 v120, v132, 0x3e38aa3b, v120
	v_cndmask_b32_e32 v132, v235, v120, vcc
	v_add_u32_e32 v120, 17, v136
	v_fmac_f32_e32 v121, 0x3e38aa3b, v133
	v_cmp_le_u32_e32 vcc, v120, v216
	v_add_u32_e32 v120, 0x1348, v125
	v_add_u32_e32 v133, 18, v136
	v_cndmask_b32_e32 v131, v235, v121, vcc
	ds_read2_b32 v[120:121], v120 offset1:1
	v_cmp_le_u32_e32 vcc, v133, v216
	v_max3_f32 v137, v137, v132, v131
	s_waitcnt lgkmcnt(0)
	v_fmamk_f32 v120, v134, 0x3e38aa3b, v120
	v_cndmask_b32_e32 v134, v235, v120, vcc
	v_add_u32_e32 v120, 19, v136
	v_fmac_f32_e32 v121, 0x3e38aa3b, v135
	v_cmp_le_u32_e32 vcc, v120, v216
	s_nop 1
	v_cndmask_b32_e32 v133, v235, v121, vcc
	v_max3_f32 v120, v137, v134, v133
	v_sub_f32_e32 v121, v120, v116
	v_cmp_lt_f32_e32 vcc, s19, v121
	s_cbranch_vccz .LBB0_506
	ds_bpermute_b32 v121, v207, v120
	v_max_f32_e32 v120, v120, v120
	s_waitcnt lgkmcnt(0)
	v_max_f32_e32 v121, v121, v121
	v_max_f32_e32 v120, v120, v121
	ds_bpermute_b32 v121, v206, v120
	s_waitcnt lgkmcnt(0)
	v_max3_f32 v120, v116, v120, v121
	v_sub_f32_e32 v116, v116, v120
	v_exp_f32_e32 v116, v116
	v_mov_b32_e32 v121, v117
	v_mul_f32_e32 v114, v114, v116
	v_pk_mul_f32 v[78:79], v[78:79], v[116:117] op_sel_hi:[1,0]
	v_pk_mul_f32 v[76:77], v[76:77], v[116:117] op_sel_hi:[1,0]
	v_pk_mul_f32 v[74:75], v[74:75], v[116:117] op_sel_hi:[1,0]
	v_pk_mul_f32 v[72:73], v[72:73], v[116:117] op_sel_hi:[1,0]
	v_pk_mul_f32 v[70:71], v[70:71], v[116:117] op_sel_hi:[1,0]
	v_pk_mul_f32 v[68:69], v[68:69], v[116:117] op_sel_hi:[1,0]
	v_pk_mul_f32 v[66:67], v[66:67], v[116:117] op_sel_hi:[1,0]
	v_pk_mul_f32 v[64:65], v[64:65], v[116:117] op_sel_hi:[1,0]
	v_mov_b64_e32 v[116:117], v[120:121]
	s_branch .LBB0_507

; #define LAS __attribute__((address_space(3)))
; template <bool EDGE>
; __device__ __forceinline__ void tile_load(TileLd& L, const bf16_t* kp, const bf16_t* vp, int S, int pos0, int dil, int k0, int lane) {
;     asm volatile("" : "+s"(k0), "+s"(pos0));
;     const int i16 = lane & 15, quad = lane >> 4;
; #pragma unroll
;     for (int st = 0; st < 2; ++st) { int pos = pos0 + dil * (k0 + 16 * st + i16); if (EDGE) pos = min(max(pos, 0), S - 1);
;         const bf16_t* p = kp + (long)pos * NIN + quad * 8; L.k[st][0] = *(const bf16x8*)p; L.k[st][1] = *(const bf16x8*)(p + 32); }
; #pragma unroll
;     for (int i = 0; i < 4; ++i) { int pos = pos0 + dil * (k0 + 8 * i + (lane >> 3)); if (EDGE) pos = min(max(pos, 0), S - 1);
;         L.v[i] = *(const u32x4*)(vp + (long)pos * NIN + (lane & 7) * 8); }
; }
; template <int G, bool EDGE> ...
;     asm volatile("" : "+s"(k0));
;     const int quad = lane >> 4; const f32x4 z4 = {0.f, 0.f, 0.f, 0.f};
;     bf16x8 vf[4]; stage_v_regs(L.v, vimg, lane, vf);
;     constexpr float C2 = 0.125f * LOG2E, THR = 6.0f;
;     const int kb = k0 + 4 * quad;
; #pragma unroll
;     for (int g = 0; g < G; ++g) {
;         const LAS float* lutb = lut + (kb - ua[g] + R);
;         float sc[8]; float mx = -1e30f;
; #pragma unroll
;         for (int st = 0; st < 2; ++st) { f32x4 s = MFMA16(L.k[st][0], q[g][0], z4); s = MFMA16(L.k[st][1], q[g][1], s);
; #pragma unroll
;             for (int jj = 0; jj < 4; ++jj) { const int c = 16 * st + jj; const bool v = (unsigned)(kb - klo[g] + c) <= (unsigned)kspan[g];
;                 float x = s[jj] * C2 + lutb[g * lutstride + c]; x = v ? x : -1e30f; sc[4 * st + jj] = x; mx = fmaxf(mx, x); } }
;         if (__any(mx - m[g] > THR)) {
;             mx = fmaxf(mx, shx(mx, 16, lane)); mx = fmaxf(mx, shx(mx, 32, lane));
;             const float mn = fmaxf(m[g], mx), al = ex2(m[g] - mn); m[g] = mn; l[g] *= al;
; #pragma unroll
;             for (int nn = 0; nn < 4; ++nn) o[g][nn] = o[g][nn] * al;
;         }
;         const float mn = m[g]; float p[8], ps = 0.f;
; #pragma unroll
;         for (int e = 0; e < 8; ++e) { p[e] = ex2(sc[e] - mn); ps += p[e]; }
;         l[g] += ps;
;         const u32x4 pw = {pg8::cvt_pk_vis(p[0], p[1]), pg8::cvt_pk_vis(p[2], p[3]), pg8::cvt_pk_vis(p[4], p[5]), pg8::cvt_pk_vis(p[6], p[7])}; const bf16x8 pf = __builtin_bit_cast(bf16x8, pw);
; #pragma unroll
.LBB0_510:
	v_sub_f32_e32 v21, v25, v20
	v_exp_f32_e32 v21, v21
	v_sub_f32_e32 v23, v24, v20
	v_exp_f32_e32 v23, v23
	v_sub_f32_e32 v24, v27, v20
	v_exp_f32_e32 v24, v24
	v_sub_f32_e32 v25, v26, v20
	v_exp_f32_e32 v25, v25
	v_sub_f32_e32 v17, v17, v20
	v_add_f32_e32 v22, 0, v21
	v_exp_f32_e32 v26, v17
	v_add_f32_e32 v22, v23, v22
	v_add_f32_e32 v22, v24, v22
	v_add_f32_e32 v22, v25, v22
	v_sub_f32_e32 v16, v16, v20
	v_add_f32_e32 v17, v26, v22
	v_exp_f32_e32 v22, v16
	s_mov_b32 s1, s8
	s_add_i32 s1, s1, s7
	v_add_f32_e32 v16, v22, v17
	v_sub_f32_e32 v17, v19, v20
	v_exp_f32_e32 v19, v17
	v_sub_f32_e32 v17, v18, v20
	v_exp_f32_e32 v20, v17
	v_cvt_pk_bf16_f32 v17, v24, v25
	v_add_f32_e32 v16, v19, v16
	v_cvt_pk_bf16_f32 v18, v26, v22
	v_add_f32_e32 v16, v20, v16
	v_add_f32_e32 v115, v115, v16
	v_cvt_pk_bf16_f32 v16, v21, v23
	v_cvt_pk_bf16_f32 v19, v19, v20
	s_waitcnt vmcnt(7)
	v_mfma_f32_16x16x32_bf16 v[128:131], v[60:63], v[8:11], 0
	v_mfma_f32_16x16x32_bf16 v[44:47], v[92:95], v[16:19], v[44:47]
	v_add_u32_e32 v92, s1, v200
	v_mfma_f32_16x16x32_bf16 v[40:43], v[80:83], v[16:19], v[40:43]
	v_med3_i32 v80, v92, 0, s70
	v_mad_u64_u32 v[80:81], s[34:35], v80, s97, v[118:119]
	v_mfma_f32_16x16x32_bf16 v[36:39], v[84:87], v[16:19], v[36:39]
	v_add_u32_e32 v84, 8, v92
	v_med3_i32 v84, v84, 0, s70
	v_mfma_f32_16x16x32_bf16 v[32:35], v[88:91], v[16:19], v[32:35]
	v_add_u32_e32 v18, s1, v199
	v_med3_i32 v16, v18, 0, s70
	v_mad_u64_u32 v[16:17], s[34:35], v16, s97, v[186:187]
	global_load_dwordx4 v[28:31], v[16:17], off offset:1536
	global_load_dwordx4 v[24:27], v[16:17], off offset:1600
	v_add_u32_e32 v16, 16, v18
	v_add_u32_e32 v88, 16, v92
	v_add_u32_e32 v92, 24, v92
	v_med3_i32 v16, v16, 0, s70
	v_med3_i32 v88, v88, 0, s70
	v_med3_i32 v92, v92, 0, s70
	v_mad_u64_u32 v[16:17], s[34:35], v16, s97, v[186:187]
	v_mad_u64_u32 v[84:85], s[34:35], v84, s97, v[118:119]
	v_mad_u64_u32 v[88:89], s[34:35], v88, s97, v[118:119]
	v_mad_u64_u32 v[92:93], s[34:35], v92, s97, v[118:119]
	global_load_dwordx4 v[20:23], v[16:17], off offset:1536
	s_nop 0
	global_load_dwordx4 v[16:19], v[16:17], off offset:1600
	s_waitcnt vmcnt(10)
	v_mfma_f32_16x16x32_bf16 v[128:131], v[56:59], v[12:15], v[128:131]
	global_load_dwordx4 v[80:83], v[80:81], off offset:3072
	s_nop 0
	global_load_dwordx4 v[84:87], v[84:85], off offset:3072
	s_nop 0
	global_load_dwordx4 v[88:91], v[88:89], off offset:3072
	s_nop 0
	global_load_dwordx4 v[92:95], v[92:93], off offset:3072
	s_waitcnt vmcnt(11)
	ds_write_b128 v122, v[96:99]
	s_waitcnt vmcnt(10)
	ds_write_b128 v122, v[100:103] offset:1152
	s_waitcnt vmcnt(9)
	ds_write_b128 v122, v[104:107] offset:2304
	s_waitcnt vmcnt(8)
	ds_write_b128 v122, v[108:111] offset:3456
	v_add_u32_e32 v126, s0, v204
	v_sub_u32_e32 v120, v126, v199
	v_lshl_add_u32 v125, v120, 2, s31
	ds_read_b64_tr_b16 v[108:109], v211
	ds_read_b64_tr_b16 v[104:105], v211 offset:32
	ds_read_b64_tr_b16 v[110:111], v211 offset:2304
	ds_read_b64_tr_b16 v[106:107], v211 offset:2336
	ds_read_b64_tr_b16 v[100:101], v211 offset:64
	ds_read_b64_tr_b16 v[102:103], v211 offset:2368
	ds_read_b64_tr_b16 v[96:97], v211 offset:96
	ds_read_b64_tr_b16 v[98:99], v211 offset:2400
	v_add_u32_e32 v123, 0x1300, v125
	ds_read2_b32 v[120:121], v123 offset1:1
	v_sub_u32_e32 v136, v126, v214
	v_cmp_le_u32_e32 vcc, v136, v216
	v_add_u32_e32 v124, 0x1308, v125
	s_waitcnt lgkmcnt(0)
	v_fmamk_f32 v120, v128, 0x3e38aa3b, v120
	v_cndmask_b32_e32 v128, v235, v120, vcc
	v_add_u32_e32 v120, 1, v136
	v_fmac_f32_e32 v121, 0x3e38aa3b, v129
	v_cmp_le_u32_e32 vcc, v120, v216
	v_add_u32_e32 v129, 2, v136
	s_nop 0
	v_cndmask_b32_e32 v127, v235, v121, vcc
	ds_read2_b32 v[120:121], v124 offset1:1
	v_cmp_le_u32_e32 vcc, v129, v216
	v_max3_f32 v132, v128, s95, v127
	s_waitcnt lgkmcnt(0)
	v_fmamk_f32 v120, v130, 0x3e38aa3b, v120
	v_cndmask_b32_e32 v130, v235, v120, vcc
	v_add_u32_e32 v120, 3, v136
	v_fmac_f32_e32 v121, 0x3e38aa3b, v131
	v_cmp_le_u32_e32 vcc, v120, v216
	v_add_u32_e32 v120, 0x1340, v125
	v_add_u32_e32 v131, 16, v136
	v_cndmask_b32_e32 v129, v235, v121, vcc
	v_max3_f32 v137, v132, v130, v129
	v_mfma_f32_16x16x32_bf16 v[132:135], v[48:51], v[8:11], 0
	ds_read2_b32 v[120:121], v120 offset1:1
	v_cmp_le_u32_e32 vcc, v131, v216
	v_mfma_f32_16x16x32_bf16 v[132:135], v[52:55], v[12:15], v[132:135]
	s_waitcnt lgkmcnt(0)
	s_nop 6
	v_fmamk_f32 v120, v132, 0x3e38aa3b, v120
	v_cndmask_b32_e32 v132, v235, v120, vcc
	v_add_u32_e32 v120, 17, v136
	v_fmac_f32_e32 v121, 0x3e38aa3b, v133
	v_cmp_le_u32_e32 vcc, v120, v216
	v_add_u32_e32 v120, 0x1348, v125
	v_add_u32_e32 v133, 18, v136
	v_cndmask_b32_e32 v131, v235, v121, vcc
	ds_read2_b32 v[120:121], v120 offset1:1
	v_cmp_le_u32_e32 vcc, v133, v216
	v_max3_f32 v137, v137, v132, v131
	s_waitcnt lgkmcnt(0)
	v_fmamk_f32 v120, v134, 0x3e38aa3b, v120
	v_cndmask_b32_e32 v134, v235, v120, vcc
	v_add_u32_e32 v120, 19, v136
	v_fmac_f32_e32 v121, 0x3e38aa3b, v135
	v_cmp_le_u32_e32 vcc, v120, v216
	s_nop 1
	v_cndmask_b32_e32 v133, v235, v121, vcc
	v_max3_f32 v120, v137, v134, v133
	v_sub_f32_e32 v121, v120, v116
	v_cmp_lt_f32_e32 vcc, s19, v121
	s_cbranch_vccz .LBB0_512
	ds_bpermute_b32 v121, v207, v120
	v_max_f32_e32 v120, v120, v120
	s_waitcnt lgkmcnt(0)
	v_max_f32_e32 v121, v121, v121
	v_max_f32_e32 v120, v120, v121
	ds_bpermute_b32 v121, v206, v120
	s_waitcnt lgkmcnt(0)
	v_max3_f32 v120, v116, v120, v121
	v_sub_f32_e32 v116, v116, v120
	v_exp_f32_e32 v116, v116
	v_mov_b32_e32 v121, v117
	v_mul_f32_e32 v114, v114, v116
	v_pk_mul_f32 v[78:79], v[78:79], v[116:117] op_sel_hi:[1,0]
	v_pk_mul_f32 v[76:77], v[76:77], v[116:117] op_sel_hi:[1,0]
	v_pk_mul_f32 v[74:75], v[74:75], v[116:117] op_sel_hi:[1,0]
	v_pk_mul_f32 v[72:73], v[72:73], v[116:117] op_sel_hi:[1,0]
	v_pk_mul_f32 v[70:71], v[70:71], v[116:117] op_sel_hi:[1,0]
	v_pk_mul_f32 v[68:69], v[68:69], v[116:117] op_sel_hi:[1,0]
	v_pk_mul_f32 v[66:67], v[66:67], v[116:117] op_sel_hi:[1,0]
	v_pk_mul_f32 v[64:65], v[64:65], v[116:117] op_sel_hi:[1,0]
	v_mov_b64_e32 v[116:117], v[120:121]
	s_branch .LBB0_513

; #define LAS __attribute__((address_space(3)))
; template <bool EDGE>
; __device__ __forceinline__ void tile_load(TileLd& L, const bf16_t* kp, const bf16_t* vp, int S, int pos0, int dil, int k0, int lane) {
;     asm volatile("" : "+s"(k0), "+s"(pos0));
;     const int i16 = lane & 15, quad = lane >> 4;
; #pragma unroll
;     for (int st = 0; st < 2; ++st) { int pos = pos0 + dil * (k0 + 16 * st + i16); if (EDGE) pos = min(max(pos, 0), S - 1);
;         const bf16_t* p = kp + (long)pos * NIN + quad * 8; L.k[st][0] = *(const bf16x8*)p; L.k[st][1] = *(const bf16x8*)(p + 32); }
; #pragma unroll
;     for (int i = 0; i < 4; ++i) { int pos = pos0 + dil * (k0 + 8 * i + (lane >> 3)); if (EDGE) pos = min(max(pos, 0), S - 1);
;         L.v[i] = *(const u32x4*)(vp + (long)pos * NIN + (lane & 7) * 8); }
; }
; template <bool EDGE>
; __device__ __forceinline__ void a2_pass2(const bf16_t* kp, const bf16_t* vp, int S, int pos0, const LAS float* lut, LAS unsigned char* vimg, int lane,
;                                          const bf16x8 (&q)[2][2], f32x4 (&o)[2][4], float (&m)[2], float (&l)[2]) {
;     const int i16 = lane & 15;
;     TileLd ta, tb; tile_load<EDGE>(ta, kp, vp, S, pos0, 4, -64, lane);
.LBB0_563:
	s_mov_b32 s7, s41
	s_movk_i32 s24, 0xffc0
	s_add_i32 s25, s7, 64
	v_add_lshl_u32 v50, s24, v199, 2
	v_add_u32_e32 v48, s7, v50
	v_med3_i32 v48, v48, 0, s70
	v_add_lshl_u32 v72, s24, v200, 2
	v_mad_u64_u32 v[48:49], s[0:1], v48, s97, v[186:187]
	v_lshlrev_b32_e32 v64, 1, v201
	v_mov_b32_e32 v65, v157
	v_add_u32_e32 v74, s7, v72
	global_load_dwordx4 v[60:63], v[48:49], off offset:1536
	global_load_dwordx4 v[56:59], v[48:49], off offset:1600
	v_add_u32_e32 v48, s25, v50
	v_lshl_add_u64 v[120:121], s[92:93], 0, v[64:65]
	v_max_i32_e32 v64, 0, v74
	v_add_u32_e32 v66, 32, v74
	v_add_u32_e32 v72, s25, v72
	v_add_u32_e32 v74, 0x60, v74
	v_med3_i32 v48, v48, 0, s70
	v_min_i32_e32 v64, s70, v64
	v_med3_i32 v66, v66, 0, s70
	v_med3_i32 v72, v72, 0, s70
	v_med3_i32 v74, v74, 0, s70
	v_mad_u64_u32 v[48:49], s[0:1], v48, s97, v[186:187]
	v_mad_u64_u32 v[64:65], s[0:1], v64, s97, v[120:121]
	v_mad_u64_u32 v[68:69], s[0:1], v66, s97, v[120:121]
	v_mad_u64_u32 v[72:73], s[0:1], v72, s97, v[120:121]
	v_mad_u64_u32 v[76:77], s[0:1], v74, s97, v[120:121]
	global_load_dwordx4 v[52:55], v[48:49], off offset:1536
	s_nop 0
	global_load_dwordx4 v[48:51], v[48:49], off offset:1600
	s_nop 0
	global_load_dwordx4 v[64:67], v[64:65], off offset:3072
	s_nop 0
	global_load_dwordx4 v[68:71], v[68:69], off offset:3072
	s_nop 0
	global_load_dwordx4 v[72:75], v[72:73], off offset:3072
	s_nop 0
	global_load_dwordx4 v[76:79], v[76:77], off offset:3072
	s_movk_i32 s0, 0xffc0
	s_mov_b32 s1, -4
	s_branch .LBB0_566

; template <bool EDGE>
; __device__ __forceinline__ void tile_load(TileLd& L, const bf16_t* kp, const bf16_t* vp, int S, int pos0, int dil, int k0, int lane) {
;     asm volatile("" : "+s"(k0), "+s"(pos0));
;     const int i16 = lane & 15, quad = lane >> 4;
; #pragma unroll
;     for (int st = 0; st < 2; ++st) { int pos = pos0 + dil * (k0 + 16 * st + i16); if (EDGE) pos = min(max(pos, 0), S - 1);
;         const bf16_t* p = kp + (long)pos * NIN + quad * 8; L.k[st][0] = *(const bf16x8*)p; L.k[st][1] = *(const bf16x8*)(p + 32); }
; #pragma unroll
;     for (int i = 0; i < 4; ++i) { int pos = pos0 + dil * (k0 + 8 * i + (lane >> 3)); if (EDGE) pos = min(max(pos, 0), S - 1);
;         L.v[i] = *(const u32x4*)(vp + (long)pos * NIN + (lane & 7) * 8); }
; }
; template <int G, bool EDGE> ...
;     asm volatile("" : "+s"(k0));
;     const int quad = lane >> 4; const f32x4 z4 = {0.f, 0.f, 0.f, 0.f};
;     bf16x8 vf[4]; stage_v_regs(L.v, vimg, lane, vf);
;     constexpr float C2 = 0.125f * LOG2E, THR = 6.0f;
;     const int kb = k0 + 4 * quad;
; #pragma unroll
;     for (int g = 0; g < G; ++g) {
;         const LAS float* lutb = lut + (kb - ua[g] + R);
;         float sc[8]; float mx = -1e30f;
; #pragma unroll
;         for (int st = 0; st < 2; ++st) { f32x4 s = MFMA16(L.k[st][0], q[g][0], z4); s = MFMA16(L.k[st][1], q[g][1], s);
; #pragma unroll
;             for (int jj = 0; jj < 4; ++jj) { const int c = 16 * st + jj; const bool v = (unsigned)(kb - klo[g] + c) <= (unsigned)kspan[g];
;                 float x = s[jj] * C2 + lutb[g * lutstride + c]; x = v ? x : -1e30f; sc[4 * st + jj] = x; mx = fmaxf(mx, x); } }
;         if (__any(mx - m[g] > THR)) {
;             mx = fmaxf(mx, shx(mx, 16, lane)); mx = fmaxf(mx, shx(mx, 32, lane));
;             const float mn = fmaxf(m[g], mx), al = ex2(m[g] - mn); m[g] = mn; l[g] *= al;
; #pragma unroll
;             for (int nn = 0; nn < 4; ++nn) o[g][nn] = o[g][nn] * al;
;         }
; template <bool EDGE>
; __device__ __forceinline__ void a2_pass2(const bf16_t* kp, const bf16_t* vp, int S, int pos0, const LAS float* lut, LAS unsigned char* vimg, int lane,
;                                          const bf16x8 (&q)[2][2], f32x4 (&o)[2][4], float (&m)[2], float (&l)[2]) {
;     ...
;     {
;         const int ua1[2] = {4 * i16, 4 * i16 + 2}; const int kmin1 = -(pos0 >> 2), kmax1 = (S - 1 - pos0) >> 2;
.LBB0_566:
	s_add_i32 s24, s0, 32
	s_mov_b32 s7, s24
	s_mov_b32 s25, s41
	s_add_i32 s36, s25, 64
	v_add_lshl_u32 v82, s7, v199, 2
	v_add_u32_e32 v80, s25, v82
	v_med3_i32 v80, v80, 0, s70
	v_add_lshl_u32 v104, s7, v200, 2
	v_mad_u64_u32 v[80:81], s[34:35], v80, s97, v[186:187]
	v_add_u32_e32 v108, s25, v104
	global_load_dwordx4 v[92:95], v[80:81], off offset:1536
	global_load_dwordx4 v[88:91], v[80:81], off offset:1600
	v_add_u32_e32 v80, s36, v82
	v_max_i32_e32 v96, 0, v108
	v_add_u32_e32 v100, 32, v108
	v_add_u32_e32 v104, s36, v104
	v_add_u32_e32 v108, 0x60, v108
	v_med3_i32 v80, v80, 0, s70
	v_min_i32_e32 v96, s70, v96
	v_med3_i32 v100, v100, 0, s70
	v_med3_i32 v104, v104, 0, s70
	v_med3_i32 v108, v108, 0, s70
	v_mad_u64_u32 v[84:85], s[34:35], v80, s97, v[186:187]
	v_mad_u64_u32 v[96:97], s[34:35], v96, s97, v[120:121]
	v_mad_u64_u32 v[100:101], s[34:35], v100, s97, v[120:121]
	v_mad_u64_u32 v[104:105], s[34:35], v104, s97, v[120:121]
	v_mad_u64_u32 v[108:109], s[34:35], v108, s97, v[120:121]
	global_load_dwordx4 v[80:83], v[84:85], off offset:1536
	s_nop 0
	global_load_dwordx4 v[84:87], v[84:85], off offset:1600
	s_mov_b32 s7, s0
	global_load_dwordx4 v[96:99], v[96:97], off offset:3072
	v_add_u32_e32 v122, v210, v203
	global_load_dwordx4 v[100:103], v[100:101], off offset:3072
	s_nop 0
	global_load_dwordx4 v[104:107], v[104:105], off offset:3072
	s_nop 0
	global_load_dwordx4 v[108:111], v[108:109], off offset:3072
	s_waitcnt vmcnt(11)
	ds_write_b128 v122, v[64:67]
	s_waitcnt vmcnt(10)
	ds_write_b128 v122, v[68:71] offset:1152
	s_waitcnt vmcnt(9)
	ds_write_b128 v122, v[72:75] offset:2304
	s_waitcnt vmcnt(8)
	ds_write_b128 v122, v[76:79] offset:3456
	v_add_u32_e32 v117, s7, v204
	v_sub_u32_e32 v112, v117, v212
	v_lshl_add_u32 v116, v112, 2, s31
	v_mfma_f32_16x16x32_bf16 v[112:115], v[60:63], v[12:15], 0
	ds_read_b64_tr_b16 v[76:77], v211
	ds_read_b64_tr_b16 v[64:65], v211 offset:32
	ds_read_b64_tr_b16 v[78:79], v211 offset:2304
	ds_read_b64_tr_b16 v[66:67], v211 offset:2336
	ds_read_b64_tr_b16 v[68:69], v211 offset:64
	ds_read_b64_tr_b16 v[70:71], v211 offset:2368
	ds_read_b64_tr_b16 v[72:73], v211 offset:96
	ds_read_b64_tr_b16 v[74:75], v211 offset:2400
	v_add_u32_e32 v118, 0x1504, v116
	v_mfma_f32_16x16x32_bf16 v[124:127], v[56:59], v[8:11], v[112:115]
	v_sub_u32_e32 v130, v117, v226
	v_cmp_le_u32_e32 vcc, v130, v228
	v_add_u32_e32 v123, 2, v130
	ds_read2_b32 v[112:113], v118 offset1:1
	s_waitcnt lgkmcnt(0)
	s_nop 2
	v_fmamk_f32 v114, v124, 0x3e38aa3b, v112
	v_cndmask_b32_e32 v119, v235, v114, vcc
	v_add_u32_e32 v114, 1, v130
	v_cmp_le_u32_e32 vcc, v114, v228
	v_add_u32_e32 v114, 0x150c, v116
	ds_read2_b32 v[114:115], v114 offset1:1
	v_fmamk_f32 v113, v125, 0x3e38aa3b, v113
	v_cndmask_b32_e32 v118, v235, v113, vcc
	v_cmp_le_u32_e32 vcc, v123, v228
	v_max3_f32 v113, v119, s95, v118
	s_waitcnt lgkmcnt(0)
	v_fmamk_f32 v114, v126, 0x3e38aa3b, v114
	v_cndmask_b32_e32 v124, v235, v114, vcc
	v_add_u32_e32 v114, 3, v130
	v_fmac_f32_e32 v115, 0x3e38aa3b, v127
	v_cmp_le_u32_e32 vcc, v114, v228
	v_mfma_f32_16x16x32_bf16 v[126:129], v[52:55], v[12:15], 0
	v_add_u32_e32 v125, 16, v130
	v_cndmask_b32_e32 v123, v235, v115, vcc
	v_max3_f32 v131, v113, v124, v123
	v_add_u32_e32 v113, 0x1544, v116
	ds_read2_b32 v[114:115], v113 offset1:1
	v_mfma_f32_16x16x32_bf16 v[126:129], v[48:51], v[8:11], v[126:129]
	v_cmp_le_u32_e32 vcc, v125, v228
	s_waitcnt lgkmcnt(0)
	s_nop 5
	v_fmamk_f32 v114, v126, 0x3e38aa3b, v114
	v_cndmask_b32_e32 v126, v235, v114, vcc
	v_add_u32_e32 v114, 17, v130
	v_fmac_f32_e32 v115, 0x3e38aa3b, v127
	v_cmp_le_u32_e32 vcc, v114, v228
	v_add_u32_e32 v114, 0x154c, v116
	v_add_u32_e32 v127, 18, v130
	v_cndmask_b32_e32 v125, v235, v115, vcc
	ds_read2_b32 v[114:115], v114 offset1:1
	v_cmp_le_u32_e32 vcc, v127, v228
	v_max3_f32 v131, v131, v126, v125
	s_waitcnt lgkmcnt(0)
	v_fmamk_f32 v114, v128, 0x3e38aa3b, v114
	v_cndmask_b32_e32 v128, v235, v114, vcc
	v_add_u32_e32 v114, 19, v130
	v_fmac_f32_e32 v115, 0x3e38aa3b, v129
	v_cmp_le_u32_e32 vcc, v114, v228
	s_nop 1
	v_cndmask_b32_e32 v127, v235, v115, vcc
	v_max3_f32 v114, v131, v128, v127
	v_sub_f32_e32 v115, v114, v190
	v_cmp_lt_f32_e32 vcc, s19, v115
	s_cbranch_vccz .LBB0_568
	ds_bpermute_b32 v115, v207, v114
	v_max_f32_e32 v114, v114, v114
	s_waitcnt lgkmcnt(0)
	v_max_f32_e32 v115, v115, v115
	v_max_f32_e32 v114, v114, v115
	ds_bpermute_b32 v115, v206, v114
	s_waitcnt lgkmcnt(0)
	v_max3_f32 v114, v190, v114, v115
	v_sub_f32_e32 v115, v190, v114
	v_exp_f32_e32 v130, v115
	v_mov_b32_e32 v115, v191
	v_mov_b64_e32 v[190:191], v[114:115]
	v_mul_f32_e32 v188, v188, v130
	v_pk_mul_f32 v[38:39], v[38:39], v[130:131] op_sel_hi:[1,0]
	v_pk_mul_f32 v[36:37], v[36:37], v[130:131] op_sel_hi:[1,0]
	v_pk_mul_f32 v[34:35], v[34:35], v[130:131] op_sel_hi:[1,0]
	v_pk_mul_f32 v[32:33], v[32:33], v[130:131] op_sel_hi:[1,0]
	v_pk_mul_f32 v[46:47], v[46:47], v[130:131] op_sel_hi:[1,0]
	v_pk_mul_f32 v[44:45], v[44:45], v[130:131] op_sel_hi:[1,0]
	v_pk_mul_f32 v[42:43], v[42:43], v[130:131] op_sel_hi:[1,0]
	v_pk_mul_f32 v[40:41], v[40:41], v[130:131] op_sel_hi:[1,0]
	s_branch .LBB0_569

; #define LAS __attribute__((address_space(3)))
; template <bool EDGE>
; __device__ __forceinline__ void tile_load(TileLd& L, const bf16_t* kp, const bf16_t* vp, int S, int pos0, int dil, int k0, int lane) {
;     asm volatile("" : "+s"(k0), "+s"(pos0));
;     const int i16 = lane & 15, quad = lane >> 4;
; #pragma unroll
;     for (int st = 0; st < 2; ++st) { int pos = pos0 + dil * (k0 + 16 * st + i16); if (EDGE) pos = min(max(pos, 0), S - 1);
;         const bf16_t* p = kp + (long)pos * NIN + quad * 8; L.k[st][0] = *(const bf16x8*)p; L.k[st][1] = *(const bf16x8*)(p + 32); }
; #pragma unroll
;     for (int i = 0; i < 4; ++i) { int pos = pos0 + dil * (k0 + 8 * i + (lane >> 3)); if (EDGE) pos = min(max(pos, 0), S - 1);
;         L.v[i] = *(const u32x4*)(vp + (long)pos * NIN + (lane & 7) * 8); }
; }
; template <int G, bool EDGE> ...
;     asm volatile("" : "+s"(k0));
;     const int quad = lane >> 4; const f32x4 z4 = {0.f, 0.f, 0.f, 0.f};
;     bf16x8 vf[4]; stage_v_regs(L.v, vimg, lane, vf);
;     constexpr float C2 = 0.125f * LOG2E, THR = 6.0f;
;     const int kb = k0 + 4 * quad;
; #pragma unroll
;     for (int g = 0; g < G; ++g) {
;         const LAS float* lutb = lut + (kb - ua[g] + R);
;         float sc[8]; float mx = -1e30f;
; #pragma unroll
;         for (int st = 0; st < 2; ++st) { f32x4 s = MFMA16(L.k[st][0], q[g][0], z4); s = MFMA16(L.k[st][1], q[g][1], s);
; #pragma unroll
;             for (int jj = 0; jj < 4; ++jj) { const int c = 16 * st + jj; const bool v = (unsigned)(kb - klo[g] + c) <= (unsigned)kspan[g];
;                 float x = s[jj] * C2 + lutb[g * lutstride + c]; x = v ? x : -1e30f; sc[4 * st + jj] = x; mx = fmaxf(mx, x); } }
;         if (__any(mx - m[g] > THR)) {
;             mx = fmaxf(mx, shx(mx, 16, lane)); mx = fmaxf(mx, shx(mx, 32, lane));
;             const float mn = fmaxf(m[g], mx), al = ex2(m[g] - mn); m[g] = mn; l[g] *= al;
; #pragma unroll
;             for (int nn = 0; nn < 4; ++nn) o[g][nn] = o[g][nn] * al;
;         }
;         const float mn = m[g]; float p[8], ps = 0.f;
; #pragma unroll
;         for (int e = 0; e < 8; ++e) { p[e] = ex2(sc[e] - mn); ps += p[e]; }
;         l[g] += ps;
;         const u32x4 pw = {pg8::cvt_pk_vis(p[0], p[1]), pg8::cvt_pk_vis(p[2], p[3]), pg8::cvt_pk_vis(p[4], p[5]), pg8::cvt_pk_vis(p[6], p[7])}; const bf16x8 pf = __builtin_bit_cast(bf16x8, pw);
; #pragma unroll
.LBB0_572:
	v_sub_f32_e32 v53, v59, v52
	v_exp_f32_e32 v53, v53
	v_sub_f32_e32 v55, v58, v52
	v_exp_f32_e32 v55, v55
	v_sub_f32_e32 v57, v57, v52
	v_exp_f32_e32 v57, v57
	v_sub_f32_e32 v56, v56, v52
	v_exp_f32_e32 v56, v56
	v_sub_f32_e32 v49, v49, v52
	v_add_f32_e32 v54, 0, v53
	v_exp_f32_e32 v58, v49
	v_add_f32_e32 v54, v55, v54
	v_add_f32_e32 v54, v57, v54
	v_add_f32_e32 v54, v56, v54
	v_sub_f32_e32 v48, v48, v52
	v_add_f32_e32 v49, v58, v54
	v_exp_f32_e32 v54, v48
	s_add_i32 s7, s1, 4
	s_add_i32 s25, s1, 6
	s_cmp_lt_u32 s7, 4
	v_add_f32_e32 v48, v54, v49
	v_sub_f32_e32 v49, v51, v52
	v_exp_f32_e32 v51, v49
	v_sub_f32_e32 v49, v50, v52
	v_exp_f32_e32 v52, v49
	s_cselect_b32 s25, s25, s1
	v_add_f32_e32 v48, v51, v48
	s_cselect_b32 s36, 2, 4
	v_add_f32_e32 v48, v52, v48
	s_lshl_b32 s25, s25, 5
	v_add_f32_e32 v189, v189, v48
	v_cvt_pk_bf16_f32 v48, v53, v55
	v_cvt_pk_bf16_f32 v49, v57, v56
	v_cvt_pk_bf16_f32 v50, v58, v54
	v_cvt_pk_bf16_f32 v51, v51, v52
	s_sub_i32 s25, s25, 64
	s_mov_b32 s37, s41
	v_mfma_f32_16x16x32_bf16 v[28:31], v[76:79], v[48:51], v[28:31]
	s_nop 0
	v_add_u32_e32 v76, s25, v200
	v_mfma_f32_16x16x32_bf16 v[20:23], v[64:67], v[48:51], v[20:23]
	v_lshlrev_b32_e32 v64, s36, v76
	v_add_u32_e32 v64, s37, v64
	v_max_i32_e32 v64, 0, v64
	v_mfma_f32_16x16x32_bf16 v[24:27], v[68:71], v[48:51], v[24:27]
	v_add_lshl_u32 v68, v76, 8, s36
	v_add_u32_e32 v68, s37, v68
	v_max_i32_e32 v68, 0, v68
	v_mfma_f32_16x16x32_bf16 v[16:19], v[72:75], v[48:51], v[16:19]
	v_add_u32_e32 v50, s25, v199
	v_lshlrev_b32_e32 v48, s36, v50
	v_add_u32_e32 v48, s37, v48
	v_med3_i32 v48, v48, 0, s70
	v_mad_u64_u32 v[48:49], s[34:35], v48, s97, v[186:187]
	global_load_dwordx4 v[60:63], v[48:49], off offset:1536
	global_load_dwordx4 v[56:59], v[48:49], off offset:1600
	v_add_lshl_u32 v48, v50, 16, s36
	v_add_lshl_u32 v72, v76, 16, s36
	v_add_lshl_u32 v76, v76, 24, s36
	v_add_u32_e32 v48, s37, v48
	v_add_u32_e32 v72, s37, v72
	v_add_u32_e32 v76, s37, v76
	v_med3_i32 v48, v48, 0, s70
	v_min_i32_e32 v64, s70, v64
	v_min_i32_e32 v68, s70, v68
	v_med3_i32 v72, v72, 0, s70
	v_med3_i32 v76, v76, 0, s70
	v_mad_u64_u32 v[48:49], s[34:35], v48, s97, v[186:187]
	v_mad_u64_u32 v[64:65], s[34:35], v64, s97, v[120:121]
	v_mad_u64_u32 v[68:69], s[34:35], v68, s97, v[120:121]
	v_mad_u64_u32 v[72:73], s[34:35], v72, s97, v[120:121]
	v_mad_u64_u32 v[76:77], s[34:35], v76, s97, v[120:121]
	global_load_dwordx4 v[52:55], v[48:49], off offset:1536
	s_nop 0
	global_load_dwordx4 v[48:51], v[48:49], off offset:1600
	s_nop 0
	global_load_dwordx4 v[64:67], v[64:65], off offset:3072
	s_nop 0
	global_load_dwordx4 v[68:71], v[68:69], off offset:3072
	s_nop 0
	global_load_dwordx4 v[72:75], v[72:73], off offset:3072
	s_nop 0
	global_load_dwordx4 v[76:79], v[76:77], off offset:3072
	s_waitcnt vmcnt(11)
	ds_write_b128 v122, v[96:99]
	s_waitcnt vmcnt(10)
	ds_write_b128 v122, v[100:103] offset:1152
	s_waitcnt vmcnt(9)
	ds_write_b128 v122, v[104:107] offset:2304
	s_waitcnt vmcnt(8)
	ds_write_b128 v122, v[108:111] offset:3456
	v_add_u32_e32 v117, s24, v204
	v_sub_u32_e32 v112, v117, v212
	v_lshl_add_u32 v116, v112, 2, s31
	v_mfma_f32_16x16x32_bf16 v[112:115], v[92:95], v[12:15], 0
	ds_read_b64_tr_b16 v[108:109], v211
	ds_read_b64_tr_b16 v[104:105], v211 offset:32
	ds_read_b64_tr_b16 v[110:111], v211 offset:2304
	ds_read_b64_tr_b16 v[106:107], v211 offset:2336
	ds_read_b64_tr_b16 v[96:97], v211 offset:64
	ds_read_b64_tr_b16 v[98:99], v211 offset:2368
	ds_read_b64_tr_b16 v[100:101], v211 offset:96
	ds_read_b64_tr_b16 v[102:103], v211 offset:2400
	v_add_u32_e32 v118, 0x1504, v116
	v_mfma_f32_16x16x32_bf16 v[124:127], v[88:91], v[8:11], v[112:115]
	v_sub_u32_e32 v130, v117, v226
	v_cmp_le_u32_e32 vcc, v130, v228
	v_add_u32_e32 v123, 2, v130
	ds_read2_b32 v[112:113], v118 offset1:1
	s_waitcnt lgkmcnt(0)
	s_nop 2
	v_fmamk_f32 v114, v124, 0x3e38aa3b, v112
	v_cndmask_b32_e32 v119, v235, v114, vcc
	v_add_u32_e32 v114, 1, v130
	v_cmp_le_u32_e32 vcc, v114, v228
	v_add_u32_e32 v114, 0x150c, v116
	ds_read2_b32 v[114:115], v114 offset1:1
	v_fmamk_f32 v113, v125, 0x3e38aa3b, v113
	v_cndmask_b32_e32 v118, v235, v113, vcc
	v_cmp_le_u32_e32 vcc, v123, v228
	v_max3_f32 v113, v119, s95, v118
	s_waitcnt lgkmcnt(0)
	v_fmamk_f32 v114, v126, 0x3e38aa3b, v114
	v_cndmask_b32_e32 v124, v235, v114, vcc
	v_add_u32_e32 v114, 3, v130
	v_fmac_f32_e32 v115, 0x3e38aa3b, v127
	v_cmp_le_u32_e32 vcc, v114, v228
	v_mfma_f32_16x16x32_bf16 v[126:129], v[80:83], v[12:15], 0
	v_add_u32_e32 v125, 16, v130
	v_cndmask_b32_e32 v123, v235, v115, vcc
	v_max3_f32 v131, v113, v124, v123
	v_add_u32_e32 v113, 0x1544, v116
	ds_read2_b32 v[114:115], v113 offset1:1
	v_mfma_f32_16x16x32_bf16 v[126:129], v[84:87], v[8:11], v[126:129]
	v_cmp_le_u32_e32 vcc, v125, v228
	s_waitcnt lgkmcnt(0)
	s_nop 5
	v_fmamk_f32 v114, v126, 0x3e38aa3b, v114
	v_cndmask_b32_e32 v126, v235, v114, vcc
	v_add_u32_e32 v114, 17, v130
	v_fmac_f32_e32 v115, 0x3e38aa3b, v127
	v_cmp_le_u32_e32 vcc, v114, v228
	v_add_u32_e32 v114, 0x154c, v116
	v_add_u32_e32 v127, 18, v130
	v_cndmask_b32_e32 v125, v235, v115, vcc
	ds_read2_b32 v[114:115], v114 offset1:1
	v_cmp_le_u32_e32 vcc, v127, v228
	v_max3_f32 v131, v131, v126, v125
	s_waitcnt lgkmcnt(0)
	v_fmamk_f32 v114, v128, 0x3e38aa3b, v114
	v_cndmask_b32_e32 v128, v235, v114, vcc
	v_add_u32_e32 v114, 19, v130
	v_fmac_f32_e32 v115, 0x3e38aa3b, v129
	v_cmp_le_u32_e32 vcc, v114, v228
	s_nop 1
	v_cndmask_b32_e32 v127, v235, v115, vcc
	v_max3_f32 v114, v131, v128, v127
	v_sub_f32_e32 v115, v114, v190
	v_cmp_lt_f32_e32 vcc, s19, v115
	s_cbranch_vccz .LBB0_574
	ds_bpermute_b32 v115, v207, v114
	v_max_f32_e32 v114, v114, v114
	s_waitcnt lgkmcnt(0)
	v_max_f32_e32 v115, v115, v115
	v_max_f32_e32 v114, v114, v115
	ds_bpermute_b32 v115, v206, v114
	s_waitcnt lgkmcnt(0)
	v_max3_f32 v114, v190, v114, v115
	v_sub_f32_e32 v115, v190, v114
	v_exp_f32_e32 v130, v115
	v_mov_b32_e32 v115, v191
	v_mov_b64_e32 v[190:191], v[114:115]
	v_mul_f32_e32 v188, v188, v130
	v_pk_mul_f32 v[38:39], v[38:39], v[130:131] op_sel_hi:[1,0]
	v_pk_mul_f32 v[36:37], v[36:37], v[130:131] op_sel_hi:[1,0]
	v_pk_mul_f32 v[34:35], v[34:35], v[130:131] op_sel_hi:[1,0]
	v_pk_mul_f32 v[32:33], v[32:33], v[130:131] op_sel_hi:[1,0]
	v_pk_mul_f32 v[44:45], v[44:45], v[130:131] op_sel_hi:[1,0]
	v_pk_mul_f32 v[46:47], v[46:47], v[130:131] op_sel_hi:[1,0]
	v_pk_mul_f32 v[40:41], v[40:41], v[130:131] op_sel_hi:[1,0]
	v_pk_mul_f32 v[42:43], v[42:43], v[130:131] op_sel_hi:[1,0]
	s_branch .LBB0_575

; template <bool EDGE>
; __device__ __forceinline__ void tile_load(TileLd& L, const bf16_t* kp, const bf16_t* vp, int S, int pos0, int dil, int k0, int lane) {
;     asm volatile("" : "+s"(k0), "+s"(pos0));
;     const int i16 = lane & 15, quad = lane >> 4;
; #pragma unroll
;     for (int st = 0; st < 2; ++st) { int pos = pos0 + dil * (k0 + 16 * st + i16); if (EDGE) pos = min(max(pos, 0), S - 1);
;         const bf16_t* p = kp + (long)pos * NIN + quad * 8; L.k[st][0] = *(const bf16x8*)p; L.k[st][1] = *(const bf16x8*)(p + 32); }
; #pragma unroll
;     for (int i = 0; i < 4; ++i) { int pos = pos0 + dil * (k0 + 8 * i + (lane >> 3)); if (EDGE) pos = min(max(pos, 0), S - 1);
;         L.v[i] = *(const u32x4*)(vp + (long)pos * NIN + (lane & 7) * 8); }
; }
; template <int G, bool EDGE> ...
;     asm volatile("" : "+s"(k0));
;     const int quad = lane >> 4; const f32x4 z4 = {0.f, 0.f, 0.f, 0.f};
;     bf16x8 vf[4]; stage_v_regs(L.v, vimg, lane, vf);
;     constexpr float C2 = 0.125f * LOG2E, THR = 6.0f;
;     const int kb = k0 + 4 * quad;
; #pragma unroll
;     for (int g = 0; g < G; ++g) {
;         const LAS float* lutb = lut + (kb - ua[g] + R);
;         float sc[8]; float mx = -1e30f;
; #pragma unroll
;         for (int st = 0; st < 2; ++st) { f32x4 s = MFMA16(L.k[st][0], q[g][0], z4); s = MFMA16(L.k[st][1], q[g][1], s);
; #pragma unroll
;             for (int jj = 0; jj < 4; ++jj) { const int c = 16 * st + jj; const bool v = (unsigned)(kb - klo[g] + c) <= (unsigned)kspan[g];
;                 float x = s[jj] * C2 + lutb[g * lutstride + c]; x = v ? x : -1e30f; sc[4 * st + jj] = x; mx = fmaxf(mx, x); } }
;         if (__any(mx - m[g] > THR)) {
;             mx = fmaxf(mx, shx(mx, 16, lane)); mx = fmaxf(mx, shx(mx, 32, lane));
;             const float mn = fmaxf(m[g], mx), al = ex2(m[g] - mn); m[g] = mn; l[g] *= al;
; #pragma unroll
;             for (int nn = 0; nn < 4; ++nn) o[g][nn] = o[g][nn] * al;
;         }
; template <bool EDGE>
; __device__ __forceinline__ void a2_pass2(const bf16_t* kp, const bf16_t* vp, int S, int pos0, const LAS float* lut, LAS unsigned char* vimg, int lane,
;                                          const bf16x8 (&q)[2][2], f32x4 (&o)[2][4], float (&m)[2], float (&l)[2]) {
;     ...
;     const int ua2[1] = {i16};
;     {
;         const int klo2[1] = {max(i16 - 64, -(pos0 >> 4))}, ksp2[1] = {min(i16 + 64, (S - 1 - pos0) >> 4) - klo2[0]};
.LBB0_579:
	s_sub_i32 s7, s1, 32
	s_mov_b32 s34, s7
	s_mov_b32 s35, s41
	s_waitcnt vmcnt(7)
	v_mfma_f32_16x16x32_bf16 v[60:63], v[60:63], v[12:15], 0
	v_add_u32_e32 v80, s34, v199
	v_lshl_add_u32 v82, v80, 4, s35
	v_med3_i32 v80, v82, 0, s70
	v_mad_u64_u32 v[80:81], s[24:25], v80, s97, v[186:187]
	global_load_dwordx4 v[108:111], v[80:81], off offset:1536
	global_load_dwordx4 v[104:107], v[80:81], off offset:1600
	v_add_u32_e32 v80, 0x100, v82
	v_med3_i32 v80, v80, 0, s70
	v_mad_u64_u32 v[80:81], s[24:25], v80, s97, v[186:187]
	global_load_dwordx4 v[88:91], v[80:81], off offset:1536
	global_load_dwordx4 v[92:95], v[80:81], off offset:1600
	v_add_u32_e32 v80, s34, v200
	v_lshl_add_u32 v98, v80, 4, s35
	v_max_i32_e32 v80, 0, v98
	v_add_u32_e32 v82, 0x80, v98
	v_add_u32_e32 v96, 0x100, v98
	v_add_u32_e32 v98, 0x180, v98
	v_min_i32_e32 v80, s70, v80
	v_med3_i32 v82, v82, 0, s70
	v_med3_i32 v96, v96, 0, s70
	v_med3_i32 v98, v98, 0, s70
	v_mad_u64_u32 v[80:81], s[24:25], v80, s97, v[120:121]
	v_mad_u64_u32 v[84:85], s[24:25], v82, s97, v[120:121]
	v_mad_u64_u32 v[96:97], s[24:25], v96, s97, v[120:121]
	v_mad_u64_u32 v[100:101], s[24:25], v98, s97, v[120:121]
	global_load_dwordx4 v[80:83], v[80:81], off offset:3072
	s_nop 0
	global_load_dwordx4 v[84:87], v[84:85], off offset:3072
	s_nop 0
	global_load_dwordx4 v[96:99], v[96:97], off offset:3072
	s_nop 0
	global_load_dwordx4 v[100:103], v[100:101], off offset:3072
	s_sub_i32 s24, s1, 64
	s_waitcnt vmcnt(11)
	ds_write_b128 v122, v[64:67]
	s_waitcnt vmcnt(10)
	ds_write_b128 v122, v[68:71] offset:1152
	s_waitcnt vmcnt(9)
	ds_write_b128 v122, v[72:75] offset:2304
	s_waitcnt vmcnt(8)
	ds_write_b128 v122, v[76:79] offset:3456
	v_add_u32_e32 v112, s24, v204
	v_sub_u32_e32 v113, v112, v199
	v_lshl_add_u32 v113, v113, 2, s31
	ds_read_b64_tr_b16 v[76:77], v211
	ds_read_b64_tr_b16 v[64:65], v211 offset:32
	ds_read_b64_tr_b16 v[68:69], v211 offset:64
	ds_read_b64_tr_b16 v[72:73], v211 offset:96
	ds_read_b64_tr_b16 v[78:79], v211 offset:2304
	ds_read_b64_tr_b16 v[66:67], v211 offset:2336
	ds_read_b64_tr_b16 v[70:71], v211 offset:2368
	ds_read_b64_tr_b16 v[74:75], v211 offset:2400
	v_add_u32_e32 v114, 0x1708, v113
	v_mfma_f32_16x16x32_bf16 v[58:61], v[56:59], v[8:11], v[60:63]
	ds_read2_b32 v[56:57], v114 offset1:1
	v_sub_u32_e32 v118, v112, v237
	v_add_u32_e32 v116, 0x1750, v113
	v_add_u32_e32 v62, 0x1710, v113
	v_add_u32_e32 v63, 0x1748, v113
	ds_read2_b32 v[112:113], v62 offset1:1
	ds_read2_b32 v[114:115], v63 offset1:1
	ds_read2_b32 v[116:117], v116 offset1:1
	s_waitcnt lgkmcnt(3)
	v_fmamk_f32 v56, v58, 0x3e38aa3b, v56
	v_cmp_le_u32_e32 vcc, v118, v238
	v_fmac_f32_e32 v57, 0x3e38aa3b, v59
	s_waitcnt lgkmcnt(2)
	v_fmamk_f32 v60, v60, 0x3e38aa3b, v112
	v_cndmask_b32_e32 v58, v235, v56, vcc
	v_add_u32_e32 v56, 1, v118
	v_cmp_le_u32_e32 vcc, v56, v238
	v_add_u32_e32 v56, 2, v118
	v_fmac_f32_e32 v113, 0x3e38aa3b, v61
	v_cndmask_b32_e32 v57, v235, v57, vcc
	v_cmp_le_u32_e32 vcc, v56, v238
	v_add_u32_e32 v112, 3, v118
	v_max3_f32 v59, v58, s95, v57
	v_cndmask_b32_e32 v56, v235, v60, vcc
	v_mfma_f32_16x16x32_bf16 v[60:63], v[52:55], v[12:15], 0
	v_cmp_le_u32_e32 vcc, v112, v238
	v_mfma_f32_16x16x32_bf16 v[60:63], v[48:51], v[8:11], v[60:63]
	v_add_u32_e32 v48, 16, v118
	v_cndmask_b32_e32 v52, v235, v113, vcc
	v_cmp_le_u32_e32 vcc, v48, v238
	v_add_u32_e32 v48, 17, v118
	v_max3_f32 v53, v59, v56, v52
	s_waitcnt lgkmcnt(1)
	s_nop 1
	v_fmamk_f32 v49, v60, 0x3e38aa3b, v114
	v_cndmask_b32_e32 v51, v235, v49, vcc
	v_fmac_f32_e32 v115, 0x3e38aa3b, v61
	v_cmp_le_u32_e32 vcc, v48, v238
	v_add_u32_e32 v48, 18, v118
	s_waitcnt lgkmcnt(0)
	v_fmamk_f32 v49, v62, 0x3e38aa3b, v116
	v_cndmask_b32_e32 v50, v235, v115, vcc
	v_cmp_le_u32_e32 vcc, v48, v238
	v_add_u32_e32 v48, 19, v118
	v_fmac_f32_e32 v117, 0x3e38aa3b, v63
	v_cndmask_b32_e32 v49, v235, v49, vcc
	v_cmp_le_u32_e32 vcc, v48, v238
	v_max3_f32 v53, v53, v51, v50
	s_nop 0
	v_cndmask_b32_e32 v48, v235, v117, vcc
	v_max3_f32 v53, v53, v49, v48
	v_sub_f32_e32 v54, v53, v190
	v_cmp_lt_f32_e32 vcc, s19, v54
	s_cbranch_vccz .LBB0_581
	ds_bpermute_b32 v54, v207, v53
	v_max_f32_e32 v53, v53, v53
	s_waitcnt lgkmcnt(0)
	v_max_f32_e32 v54, v54, v54
	v_max_f32_e32 v53, v53, v54
	ds_bpermute_b32 v54, v206, v53
	s_waitcnt lgkmcnt(0)
	v_max3_f32 v53, v190, v53, v54
	v_sub_f32_e32 v54, v190, v53
	v_exp_f32_e32 v54, v54
	v_mov_b32_e32 v190, v53
	v_mul_f32_e32 v188, v188, v54
	v_pk_mul_f32 v[46:47], v[46:47], v[54:55] op_sel_hi:[1,0]
	v_pk_mul_f32 v[44:45], v[44:45], v[54:55] op_sel_hi:[1,0]
	v_pk_mul_f32 v[34:35], v[34:35], v[54:55] op_sel_hi:[1,0]
	v_pk_mul_f32 v[32:33], v[32:33], v[54:55] op_sel_hi:[1,0]
	v_pk_mul_f32 v[38:39], v[38:39], v[54:55] op_sel_hi:[1,0]
	v_pk_mul_f32 v[36:37], v[36:37], v[54:55] op_sel_hi:[1,0]
	v_pk_mul_f32 v[40:41], v[40:41], v[54:55] op_sel_hi:[1,0]
	v_pk_mul_f32 v[42:43], v[42:43], v[54:55] op_sel_hi:[1,0]
; #define LAS __attribute__((address_space(3)))
; template <bool EDGE>
; __device__ __forceinline__ void tile_load(TileLd& L, const bf16_t* kp, const bf16_t* vp, int S, int pos0, int dil, int k0, int lane) {
;     asm volatile("" : "+s"(k0), "+s"(pos0));
;     const int i16 = lane & 15, quad = lane >> 4;
; #pragma unroll
;     for (int st = 0; st < 2; ++st) { int pos = pos0 + dil * (k0 + 16 * st + i16); if (EDGE) pos = min(max(pos, 0), S - 1);
;         const bf16_t* p = kp + (long)pos * NIN + quad * 8; L.k[st][0] = *(const bf16x8*)p; L.k[st][1] = *(const bf16x8*)(p + 32); }
; #pragma unroll
;     for (int i = 0; i < 4; ++i) { int pos = pos0 + dil * (k0 + 8 * i + (lane >> 3)); if (EDGE) pos = min(max(pos, 0), S - 1);
;         L.v[i] = *(const u32x4*)(vp + (long)pos * NIN + (lane & 7) * 8); }
; }
; template <int G, bool EDGE> ...
;     asm volatile("" : "+s"(k0));
;     const int quad = lane >> 4; const f32x4 z4 = {0.f, 0.f, 0.f, 0.f};
;     bf16x8 vf[4]; stage_v_regs(L.v, vimg, lane, vf);
;     constexpr float C2 = 0.125f * LOG2E, THR = 6.0f;
;     const int kb = k0 + 4 * quad;
; #pragma unroll
;     for (int g = 0; g < G; ++g) {
;         const LAS float* lutb = lut + (kb - ua[g] + R);
;         float sc[8]; float mx = -1e30f;
; #pragma unroll
;         for (int st = 0; st < 2; ++st) { f32x4 s = MFMA16(L.k[st][0], q[g][0], z4); s = MFMA16(L.k[st][1], q[g][1], s);
; #pragma unroll
;             for (int jj = 0; jj < 4; ++jj) { const int c = 16 * st + jj; const bool v = (unsigned)(kb - klo[g] + c) <= (unsigned)kspan[g];
;                 float x = s[jj] * C2 + lutb[g * lutstride + c]; x = v ? x : -1e30f; sc[4 * st + jj] = x; mx = fmaxf(mx, x); } }
;         if (__any(mx - m[g] > THR)) {
;             mx = fmaxf(mx, shx(mx, 16, lane)); mx = fmaxf(mx, shx(mx, 32, lane));
;             const float mn = fmaxf(m[g], mx), al = ex2(m[g] - mn); m[g] = mn; l[g] *= al;
; #pragma unroll
;             for (int nn = 0; nn < 4; ++nn) o[g][nn] = o[g][nn] * al;
;         }
;         const float mn = m[g]; float p[8], ps = 0.f;
; #pragma unroll
;         for (int e = 0; e < 8; ++e) { p[e] = ex2(sc[e] - mn); ps += p[e]; }
;         l[g] += ps;
;         const u32x4 pw = {pg8::cvt_pk_vis(p[0], p[1]), pg8::cvt_pk_vis(p[2], p[3]), pg8::cvt_pk_vis(p[4], p[5]), pg8::cvt_pk_vis(p[6], p[7])}; const bf16x8 pf = __builtin_bit_cast(bf16x8, pw);
; #pragma unroll
.LBB0_581:
	v_sub_f32_e32 v53, v58, v190
	v_exp_f32_e32 v53, v53
	v_sub_f32_e32 v55, v57, v190
	v_exp_f32_e32 v55, v55
	v_sub_f32_e32 v56, v56, v190
	v_exp_f32_e32 v56, v56
	v_sub_f32_e32 v52, v52, v190
	v_exp_f32_e32 v52, v52
	v_sub_f32_e32 v51, v51, v190
	v_add_f32_e32 v54, 0, v53
	v_exp_f32_e32 v51, v51
	v_sub_f32_e32 v50, v50, v190
	v_add_f32_e32 v54, v55, v54
	v_exp_f32_e32 v50, v50
	v_sub_f32_e32 v49, v49, v190
	v_add_f32_e32 v54, v56, v54
	v_exp_f32_e32 v57, v49
	v_add_f32_e32 v54, v52, v54
	v_add_f32_e32 v54, v51, v54
	v_add_f32_e32 v54, v50, v54
	v_sub_f32_e32 v48, v48, v190
	v_add_f32_e32 v49, v57, v54
	v_exp_f32_e32 v54, v48
	v_cvt_pk_bf16_f32 v50, v51, v50
	s_mov_b32 s34, s1
	s_mov_b32 s35, s41
	v_add_f32_e32 v48, v54, v49
	v_add_f32_e32 v112, v188, v48
	v_cvt_pk_bf16_f32 v48, v53, v55
	v_cvt_pk_bf16_f32 v49, v56, v52
	v_cvt_pk_bf16_f32 v51, v57, v54
	s_waitcnt vmcnt(7)
	v_mfma_f32_16x16x32_bf16 v[108:111], v[108:111], v[12:15], 0
	v_mfma_f32_16x16x32_bf16 v[36:39], v[76:79], v[48:51], v[36:39]
	v_mfma_f32_16x16x32_bf16 v[32:35], v[64:67], v[48:51], v[32:35]
	v_add_u32_e32 v64, s34, v200
	v_lshl_add_u32 v76, v64, 4, s35
	v_mfma_f32_16x16x32_bf16 v[44:47], v[68:71], v[48:51], v[44:47]
	v_add_u32_e32 v68, 0x80, v76
	v_max_i32_e32 v68, 0, v68
	v_med3_i32 v64, v76, 0, s70
	v_mfma_f32_16x16x32_bf16 v[40:43], v[72:75], v[48:51], v[40:43]
	v_add_u32_e32 v48, s34, v199
	v_lshl_add_u32 v50, v48, 4, s35
	v_med3_i32 v48, v50, 0, s70
	v_mad_u64_u32 v[48:49], s[24:25], v48, s97, v[186:187]
	global_load_dwordx4 v[60:63], v[48:49], off offset:1536
	global_load_dwordx4 v[56:59], v[48:49], off offset:1600
	v_add_u32_e32 v48, 0x100, v50
	v_add_u32_e32 v72, 0x100, v76
	v_add_u32_e32 v76, 0x180, v76
	v_med3_i32 v48, v48, 0, s70
	v_min_i32_e32 v68, s70, v68
	v_med3_i32 v72, v72, 0, s70
	v_med3_i32 v76, v76, 0, s70
	v_mad_u64_u32 v[48:49], s[24:25], v48, s97, v[186:187]
	v_mad_u64_u32 v[64:65], s[24:25], v64, s97, v[120:121]
	v_mad_u64_u32 v[68:69], s[24:25], v68, s97, v[120:121]
	v_mad_u64_u32 v[72:73], s[24:25], v72, s97, v[120:121]
	v_mad_u64_u32 v[76:77], s[24:25], v76, s97, v[120:121]
	global_load_dwordx4 v[52:55], v[48:49], off offset:1536
	s_nop 0
	global_load_dwordx4 v[48:51], v[48:49], off offset:1600
	s_waitcnt vmcnt(10)
	v_mfma_f32_16x16x32_bf16 v[106:109], v[104:107], v[8:11], v[108:111]
	global_load_dwordx4 v[64:67], v[64:65], off offset:3072
	s_nop 0
	global_load_dwordx4 v[68:71], v[68:69], off offset:3072
	s_waitcnt vmcnt(11)
	v_mfma_f32_16x16x32_bf16 v[88:91], v[88:91], v[12:15], 0
	global_load_dwordx4 v[72:75], v[72:73], off offset:3072
	s_nop 0
	global_load_dwordx4 v[76:79], v[76:77], off offset:3072
	s_waitcnt vmcnt(11)
	ds_write_b128 v122, v[80:83]
	s_waitcnt vmcnt(10)
	ds_write_b128 v122, v[84:87] offset:1152
	s_waitcnt vmcnt(9)
	ds_write_b128 v122, v[96:99] offset:2304
	s_waitcnt vmcnt(8)
	ds_write_b128 v122, v[100:103] offset:3456
	v_add_u32_e32 v113, s7, v204
	v_sub_u32_e32 v114, v113, v199
	v_lshl_add_u32 v114, v114, 2, s31
	ds_read_b64_tr_b16 v[100:101], v211
	ds_read_b64_tr_b16 v[96:97], v211 offset:32
	ds_read_b64_tr_b16 v[102:103], v211 offset:2304
	ds_read_b64_tr_b16 v[98:99], v211 offset:2336
	ds_read_b64_tr_b16 v[80:81], v211 offset:64
	ds_read_b64_tr_b16 v[82:83], v211 offset:2368
	ds_read_b64_tr_b16 v[84:85], v211 offset:96
	ds_read_b64_tr_b16 v[86:87], v211 offset:2400
	v_add_u32_e32 v115, 0x1708, v114
	ds_read2_b32 v[110:111], v115 offset1:1
	v_sub_u32_e32 v113, v113, v237
	v_cmp_le_u32_e32 vcc, v113, v238
	v_mfma_f32_16x16x32_bf16 v[90:93], v[92:95], v[8:11], v[88:91]
	s_waitcnt lgkmcnt(0)
	v_fmamk_f32 v104, v106, 0x3e38aa3b, v110
	v_cndmask_b32_e32 v105, v235, v104, vcc
	v_add_u32_e32 v104, 1, v113
	v_fmac_f32_e32 v111, 0x3e38aa3b, v107
	v_cmp_le_u32_e32 vcc, v104, v238
	v_add_u32_e32 v107, 0x1710, v114
	v_add_u32_e32 v89, 0x1748, v114
	v_cndmask_b32_e32 v104, v235, v111, vcc
	ds_read2_b32 v[110:111], v107 offset1:1
	ds_read2_b32 v[94:95], v89 offset1:1
	v_add_u32_e32 v106, 2, v113
	v_cmp_le_u32_e32 vcc, v106, v238
	v_add_u32_e32 v106, 3, v113
	s_waitcnt lgkmcnt(1)
	v_fmamk_f32 v107, v108, 0x3e38aa3b, v110
	v_cndmask_b32_e32 v107, v235, v107, vcc
	v_fmac_f32_e32 v111, 0x3e38aa3b, v109
	v_cmp_le_u32_e32 vcc, v106, v238
	v_add_u32_e32 v88, 16, v113
	s_waitcnt lgkmcnt(0)
	v_fmamk_f32 v89, v90, 0x3e38aa3b, v94
	v_cndmask_b32_e32 v106, v235, v111, vcc
	v_cmp_le_u32_e32 vcc, v88, v238
	v_add_u32_e32 v88, 17, v113
	v_fmac_f32_e32 v95, 0x3e38aa3b, v91
	v_cndmask_b32_e32 v89, v235, v89, vcc
	v_cmp_le_u32_e32 vcc, v88, v238
	v_add_u32_e32 v91, 0x1750, v114
	v_add_u32_e32 v90, 18, v113
	v_cndmask_b32_e32 v88, v235, v95, vcc
	ds_read2_b32 v[94:95], v91 offset1:1
	v_max3_f32 v115, v105, s95, v104
	v_cmp_le_u32_e32 vcc, v90, v238
	v_add_u32_e32 v90, 19, v113
	v_max3_f32 v108, v115, v107, v106
	s_waitcnt lgkmcnt(0)
	v_fmamk_f32 v91, v92, 0x3e38aa3b, v94
	v_cndmask_b32_e32 v91, v235, v91, vcc
	v_fmac_f32_e32 v95, 0x3e38aa3b, v93
	v_cmp_le_u32_e32 vcc, v90, v238
	v_max3_f32 v108, v108, v89, v88
	s_nop 0
	v_cndmask_b32_e32 v90, v235, v95, vcc
	v_max3_f32 v92, v108, v91, v90
	v_sub_f32_e32 v93, v92, v190
	v_cmp_lt_f32_e32 vcc, s19, v93
	s_cbranch_vccz .LBB0_578
	ds_bpermute_b32 v93, v207, v92
	v_max_f32_e32 v92, v92, v92
	s_waitcnt lgkmcnt(0)
	v_max_f32_e32 v93, v93, v93
	v_max_f32_e32 v92, v92, v93
	ds_bpermute_b32 v93, v206, v92
	s_waitcnt lgkmcnt(0)
	v_max3_f32 v93, v190, v92, v93
	v_sub_f32_e32 v92, v190, v93
	v_exp_f32_e32 v92, v92
	v_mov_b32_e32 v190, v93
	v_mul_f32_e32 v112, v112, v92
	v_pk_mul_f32 v[38:39], v[38:39], v[92:93] op_sel_hi:[1,0]
	v_pk_mul_f32 v[36:37], v[36:37], v[92:93] op_sel_hi:[1,0]
	v_pk_mul_f32 v[34:35], v[34:35], v[92:93] op_sel_hi:[1,0]
	v_pk_mul_f32 v[32:33], v[32:33], v[92:93] op_sel_hi:[1,0]
	v_pk_mul_f32 v[46:47], v[46:47], v[92:93] op_sel_hi:[1,0]
	v_pk_mul_f32 v[44:45], v[44:45], v[92:93] op_sel_hi:[1,0]
	v_pk_mul_f32 v[42:43], v[42:43], v[92:93] op_sel_hi:[1,0]
	v_pk_mul_f32 v[40:41], v[40:41], v[92:93] op_sel_hi:[1,0]
	s_branch .LBB0_578
; #define LAS __attribute__((address_space(3)))
; template <bool EDGE>
; __device__ __forceinline__ void tile_load(TileLd& L, const bf16_t* kp, const bf16_t* vp, int S, int pos0, int dil, int k0, int lane) {
;     asm volatile("" : "+s"(k0), "+s"(pos0));
;     const int i16 = lane & 15, quad = lane >> 4;
; #pragma unroll
;     for (int st = 0; st < 2; ++st) { int pos = pos0 + dil * (k0 + 16 * st + i16); if (EDGE) pos = min(max(pos, 0), S - 1);
;         const bf16_t* p = kp + (long)pos * NIN + quad * 8; L.k[st][0] = *(const bf16x8*)p; L.k[st][1] = *(const bf16x8*)(p + 32); }
; #pragma unroll
;     for (int i = 0; i < 4; ++i) { int pos = pos0 + dil * (k0 + 8 * i + (lane >> 3)); if (EDGE) pos = min(max(pos, 0), S - 1);
;         L.v[i] = *(const u32x4*)(vp + (long)pos * NIN + (lane & 7) * 8); }
; }
; template <int G, bool EDGE> ...
;     asm volatile("" : "+s"(k0));
;     const int quad = lane >> 4; const f32x4 z4 = {0.f, 0.f, 0.f, 0.f};
;     bf16x8 vf[4]; stage_v_regs(L.v, vimg, lane, vf);
;     constexpr float C2 = 0.125f * LOG2E, THR = 6.0f;
;     const int kb = k0 + 4 * quad;
; #pragma unroll
;     for (int g = 0; g < G; ++g) {
;         const LAS float* lutb = lut + (kb - ua[g] + R);
;         float sc[8]; float mx = -1e30f;
; #pragma unroll
;         for (int st = 0; st < 2; ++st) { f32x4 s = MFMA16(L.k[st][0], q[g][0], z4); s = MFMA16(L.k[st][1], q[g][1], s);
; #pragma unroll
;             for (int jj = 0; jj < 4; ++jj) { const int c = 16 * st + jj; const bool v = (unsigned)(kb - klo[g] + c) <= (unsigned)kspan[g];
;                 float x = s[jj] * C2 + lutb[g * lutstride + c]; x = v ? x : -1e30f; sc[4 * st + jj] = x; mx = fmaxf(mx, x); } }
;         if (__any(mx - m[g] > THR)) {
;             mx = fmaxf(mx, shx(mx, 16, lane)); mx = fmaxf(mx, shx(mx, 32, lane));
;             const float mn = fmaxf(m[g], mx), al = ex2(m[g] - mn); m[g] = mn; l[g] *= al;
; #pragma unroll
;             for (int nn = 0; nn < 4; ++nn) o[g][nn] = o[g][nn] * al;
;         }
;         const float mn = m[g]; float p[8], ps = 0.f;
; #pragma unroll
;         for (int e = 0; e < 8; ++e) { p[e] = ex2(sc[e] - mn); ps += p[e]; }
;         l[g] += ps;
;         const u32x4 pw = {pg8::cvt_pk_vis(p[0], p[1]), pg8::cvt_pk_vis(p[2], p[3]), pg8::cvt_pk_vis(p[4], p[5]), pg8::cvt_pk_vis(p[6], p[7])}; const bf16x8 pf = __builtin_bit_cast(bf16x8, pw);
; #pragma unroll
.LBB0_583:
	s_mov_b32 s7, s42
	s_movk_i32 s24, 0xffc0
	s_add_i32 s25, s7, 0x100
	v_add_lshl_u32 v82, s24, v199, 4
	v_add_u32_e32 v80, s7, v82
	v_med3_i32 v80, v80, 0, s70
	v_add_lshl_u32 v104, s24, v200, 4
	v_mad_u64_u32 v[80:81], s[0:1], v80, s97, v[186:187]
	v_add_u32_e32 v106, s7, v104
	global_load_dwordx4 v[92:95], v[80:81], off offset:1536
	global_load_dwordx4 v[88:91], v[80:81], off offset:1600
	v_add_u32_e32 v80, s25, v82
	v_max_i32_e32 v96, 0, v106
	v_add_u32_e32 v98, 0x80, v106
	v_add_u32_e32 v104, s25, v104
	v_add_u32_e32 v106, 0x180, v106
	v_med3_i32 v80, v80, 0, s70
	v_min_i32_e32 v96, s70, v96
	v_med3_i32 v98, v98, 0, s70
	v_med3_i32 v104, v104, 0, s70
	v_med3_i32 v106, v106, 0, s70
	v_mad_u64_u32 v[80:81], s[0:1], v80, s97, v[186:187]
	v_mad_u64_u32 v[96:97], s[0:1], v96, s97, v[120:121]
	v_mad_u64_u32 v[100:101], s[0:1], v98, s97, v[120:121]
	v_mad_u64_u32 v[104:105], s[0:1], v104, s97, v[120:121]
	v_mad_u64_u32 v[108:109], s[0:1], v106, s97, v[120:121]
	global_load_dwordx4 v[84:87], v[80:81], off offset:1536
	s_nop 0
	global_load_dwordx4 v[80:83], v[80:81], off offset:1600
	s_nop 0
	global_load_dwordx4 v[96:99], v[96:97], off offset:3072
	s_nop 0
	global_load_dwordx4 v[100:103], v[100:101], off offset:3072
	s_nop 0
	global_load_dwordx4 v[104:107], v[104:105], off offset:3072
	s_nop 0
	global_load_dwordx4 v[108:111], v[108:109], off offset:3072
	s_mov_b32 s0, 64
	s_waitcnt vmcnt(15)
	v_mfma_f32_16x16x32_bf16 v[60:63], v[60:63], v[12:15], 0
	v_add_u32_e32 v112, s0, v204
	s_waitcnt vmcnt(11)
	ds_write_b128 v122, v[64:67]
	s_waitcnt vmcnt(10)
	ds_write_b128 v122, v[68:71] offset:1152
	s_waitcnt vmcnt(9)
	ds_write_b128 v122, v[72:75] offset:2304
	s_waitcnt vmcnt(8)
	ds_write_b128 v122, v[76:79] offset:3456
	v_sub_u32_e32 v113, v112, v199
	v_lshl_add_u32 v113, v113, 2, s31
	ds_read_b64_tr_b16 v[76:77], v211
	ds_read_b64_tr_b16 v[72:73], v211 offset:32
	ds_read_b64_tr_b16 v[64:65], v211 offset:64
	ds_read_b64_tr_b16 v[68:69], v211 offset:96
	ds_read_b64_tr_b16 v[78:79], v211 offset:2304
	ds_read_b64_tr_b16 v[74:75], v211 offset:2336
	ds_read_b64_tr_b16 v[66:67], v211 offset:2368
	ds_read_b64_tr_b16 v[70:71], v211 offset:2400
	v_add_u32_e32 v114, 0x1708, v113
	v_mfma_f32_16x16x32_bf16 v[56:59], v[56:59], v[8:11], v[60:63]
	v_sub_u32_e32 v116, v112, v237
	v_add_u32_e32 v112, 0x1748, v113
	v_cmp_le_u32_e32 vcc, v116, v238
	ds_read2_b32 v[60:61], v114 offset1:1
	v_mfma_f32_16x16x32_bf16 v[52:55], v[52:55], v[12:15], 0
	v_add_u32_e32 v62, 0x1710, v113
	v_add_u32_e32 v114, 0x1750, v113
	ds_read2_b32 v[62:63], v62 offset1:1
	ds_read2_b32 v[112:113], v112 offset1:1
	ds_read2_b32 v[114:115], v114 offset1:1
	s_waitcnt lgkmcnt(3)
	v_fmamk_f32 v56, v56, 0x3e38aa3b, v60
	v_add_u32_e32 v60, 1, v116
	v_cndmask_b32_e32 v56, v235, v56, vcc
	v_fmac_f32_e32 v61, 0x3e38aa3b, v57
	v_cmp_le_u32_e32 vcc, v60, v238
	v_mfma_f32_16x16x32_bf16 v[8:11], v[48:51], v[8:11], v[52:55]
	s_waitcnt lgkmcnt(2)
	v_fmamk_f32 v58, v58, 0x3e38aa3b, v62
	v_cndmask_b32_e32 v57, v235, v61, vcc
	v_add_u32_e32 v61, 2, v116
	v_cmp_le_u32_e32 vcc, v61, v238
	v_add_u32_e32 v61, 3, v116
	v_fmac_f32_e32 v63, 0x3e38aa3b, v59
	v_cndmask_b32_e32 v58, v235, v58, vcc
	v_cmp_le_u32_e32 vcc, v61, v238
	v_add_u32_e32 v14, 16, v116
	s_waitcnt lgkmcnt(1)
	v_fmamk_f32 v8, v8, 0x3e38aa3b, v112
	v_cndmask_b32_e32 v12, v235, v63, vcc
	v_cmp_le_u32_e32 vcc, v14, v238
	v_add_u32_e32 v14, 17, v116
	v_fmac_f32_e32 v113, 0x3e38aa3b, v9
	v_cndmask_b32_e32 v8, v235, v8, vcc
	v_cmp_le_u32_e32 vcc, v14, v238
	v_add_u32_e32 v14, 18, v116
	v_max3_f32 v60, v56, s95, v57
	v_cndmask_b32_e32 v9, v235, v113, vcc
	s_waitcnt lgkmcnt(0)
	v_fmamk_f32 v10, v10, 0x3e38aa3b, v114
	v_cmp_le_u32_e32 vcc, v14, v238
	v_add_u32_e32 v14, 19, v116
	v_max3_f32 v13, v60, v58, v12
	v_cndmask_b32_e32 v10, v235, v10, vcc
	v_fmac_f32_e32 v115, 0x3e38aa3b, v11
	v_cmp_le_u32_e32 vcc, v14, v238
	v_max3_f32 v13, v13, v8, v9
	s_nop 0
	v_cndmask_b32_e32 v11, v235, v115, vcc
	v_max3_f32 v13, v13, v10, v11
	v_sub_f32_e32 v14, v13, v190
	v_cmp_lt_f32_e32 vcc, s19, v14
	s_cbranch_vccz .LBB0_585
	ds_bpermute_b32 v14, v207, v13
	v_max_f32_e32 v13, v13, v13
	s_waitcnt lgkmcnt(0)
	v_max_f32_e32 v14, v14, v14
	v_max_f32_e32 v13, v13, v14
	ds_bpermute_b32 v14, v206, v13
	s_waitcnt lgkmcnt(0)
	v_max3_f32 v13, v190, v13, v14
	v_sub_f32_e32 v14, v190, v13
	v_exp_f32_e32 v14, v14
	v_mov_b32_e32 v190, v13
	v_mul_f32_e32 v188, v188, v14
	v_pk_mul_f32 v[38:39], v[38:39], v[14:15] op_sel_hi:[1,0]
	v_pk_mul_f32 v[36:37], v[36:37], v[14:15] op_sel_hi:[1,0]
	v_pk_mul_f32 v[34:35], v[34:35], v[14:15] op_sel_hi:[1,0]
	v_pk_mul_f32 v[32:33], v[32:33], v[14:15] op_sel_hi:[1,0]
	v_pk_mul_f32 v[46:47], v[46:47], v[14:15] op_sel_hi:[1,0]
	v_pk_mul_f32 v[44:45], v[44:45], v[14:15] op_sel_hi:[1,0]
	v_pk_mul_f32 v[42:43], v[42:43], v[14:15] op_sel_hi:[1,0]
	v_pk_mul_f32 v[40:41], v[40:41], v[14:15] op_sel_hi:[1,0]

; template <bool EDGE>
; __device__ __forceinline__ void tile_load(TileLd& L, const bf16_t* kp, const bf16_t* vp, int S, int pos0, int dil, int k0, int lane) {
;     asm volatile("" : "+s"(k0), "+s"(pos0));
;     const int i16 = lane & 15, quad = lane >> 4;
; #pragma unroll
;     for (int st = 0; st < 2; ++st) { int pos = pos0 + dil * (k0 + 16 * st + i16); if (EDGE) pos = min(max(pos, 0), S - 1);
;         const bf16_t* p = kp + (long)pos * NIN + quad * 8; L.k[st][0] = *(const bf16x8*)p; L.k[st][1] = *(const bf16x8*)(p + 32); }
; #pragma unroll
;     for (int i = 0; i < 4; ++i) { int pos = pos0 + dil * (k0 + 8 * i + (lane >> 3)); if (EDGE) pos = min(max(pos, 0), S - 1);
;         L.v[i] = *(const u32x4*)(vp + (long)pos * NIN + (lane & 7) * 8); }
; }
; template <int G, bool EDGE> ...
;     asm volatile("" : "+s"(k0));
;     const int quad = lane >> 4; const f32x4 z4 = {0.f, 0.f, 0.f, 0.f};
;     bf16x8 vf[4]; stage_v_regs(L.v, vimg, lane, vf);
;     constexpr float C2 = 0.125f * LOG2E, THR = 6.0f;
;     const int kb = k0 + 4 * quad;
; #pragma unroll
;     for (int g = 0; g < G; ++g) {
;         const LAS float* lutb = lut + (kb - ua[g] + R);
;         float sc[8]; float mx = -1e30f;
; #pragma unroll
;         for (int st = 0; st < 2; ++st) { f32x4 s = MFMA16(L.k[st][0], q[g][0], z4); s = MFMA16(L.k[st][1], q[g][1], s);
; #pragma unroll
;             for (int jj = 0; jj < 4; ++jj) { const int c = 16 * st + jj; const bool v = (unsigned)(kb - klo[g] + c) <= (unsigned)kspan[g];
;                 float x = s[jj] * C2 + lutb[g * lutstride + c]; x = v ? x : -1e30f; sc[4 * st + jj] = x; mx = fmaxf(mx, x); } }
;         if (__any(mx - m[g] > THR)) {
;             mx = fmaxf(mx, shx(mx, 16, lane)); mx = fmaxf(mx, shx(mx, 32, lane));
;             const float mn = fmaxf(m[g], mx), al = ex2(m[g] - mn); m[g] = mn; l[g] *= al;
; #pragma unroll
;             for (int nn = 0; nn < 4; ++nn) o[g][nn] = o[g][nn] * al;
;         }
; template <bool EDGE>
; __device__ __forceinline__ void a2_pass2(const bf16_t* kp, const bf16_t* vp, int S, int pos0, const LAS float* lut, LAS unsigned char* vimg, int lane,
;                                          const bf16x8 (&q)[2][2], f32x4 (&o)[2][4], float (&m)[2], float (&l)[2]) {
;     ...
;     {
;         const int klo2[1] = {max(i16 - 64, -((pos0 + 8) >> 4))}, ksp2[1] = {min(i16 + 64, (S - 9 - pos0) >> 4) - klo2[0]};
.LBB0_587:
	s_sub_i32 s7, s1, 32
	s_mov_b32 s34, s7
	s_mov_b32 s35, s42
	s_waitcnt vmcnt(7)
	v_mfma_f32_16x16x32_bf16 v[92:95], v[92:95], v[4:7], 0
	v_add_u32_e32 v12, s34, v199
	v_lshl_add_u32 v14, v12, 4, s35
	v_med3_i32 v12, v14, 0, s70
	v_mad_u64_u32 v[12:13], s[24:25], v12, s97, v[186:187]
	global_load_dwordx4 v[112:115], v[12:13], off offset:1536
	global_load_dwordx4 v[60:63], v[12:13], off offset:1600
	v_add_u32_e32 v12, 0x100, v14
	v_med3_i32 v12, v12, 0, s70
	v_mad_u64_u32 v[12:13], s[24:25], v12, s97, v[186:187]
	global_load_dwordx4 v[44:47], v[12:13], off offset:1536
	global_load_dwordx4 v[48:51], v[12:13], off offset:1600
	v_add_u32_e32 v12, s34, v200
	v_lshl_add_u32 v56, v12, 4, s35
	v_add_u32_e32 v14, 0x80, v56
	v_med3_i32 v12, v56, 0, s70
	v_mad_u64_u32 v[12:13], s[24:25], v12, s97, v[120:121]
	v_med3_i32 v14, v14, 0, s70
	v_mad_u64_u32 v[14:15], s[24:25], v14, s97, v[120:121]
	global_load_dwordx4 v[40:43], v[12:13], off offset:3072
	global_load_dwordx4 v[52:55], v[14:15], off offset:3072
	v_add_u32_e32 v12, 0x100, v56
	v_add_u32_e32 v14, 0x180, v56
	v_med3_i32 v12, v12, 0, s70
	v_mad_u64_u32 v[12:13], s[24:25], v12, s97, v[120:121]
	v_med3_i32 v14, v14, 0, s70
	v_mad_u64_u32 v[14:15], s[24:25], v14, s97, v[120:121]
	global_load_dwordx4 v[56:59], v[12:13], off offset:3072
	global_load_dwordx4 v[116:119], v[14:15], off offset:3072
	s_sub_i32 s24, s1, 64
	s_waitcnt vmcnt(11)
	ds_write_b128 v122, v[96:99]
	s_waitcnt vmcnt(10)
	ds_write_b128 v122, v[100:103] offset:1152
	s_waitcnt vmcnt(9)
	ds_write_b128 v122, v[104:107] offset:2304
	s_waitcnt vmcnt(8)
	ds_write_b128 v122, v[108:111] offset:3456
	v_add_u32_e32 v108, s24, v204
	v_sub_u32_e32 v109, v108, v199
	v_lshl_add_u32 v109, v109, 2, s31
	ds_read_b64_tr_b16 v[104:105], v211
	ds_read_b64_tr_b16 v[12:13], v211 offset:32
	ds_read_b64_tr_b16 v[96:97], v211 offset:64
	ds_read_b64_tr_b16 v[100:101], v211 offset:96
	ds_read_b64_tr_b16 v[106:107], v211 offset:2304
	ds_read_b64_tr_b16 v[14:15], v211 offset:2336
	ds_read_b64_tr_b16 v[98:99], v211 offset:2368
	ds_read_b64_tr_b16 v[102:103], v211 offset:2400
	v_add_u32_e32 v110, 0x1708, v109
	v_mfma_f32_16x16x32_bf16 v[90:93], v[88:91], v[0:3], v[92:95]
	ds_read2_b32 v[88:89], v110 offset1:1
	v_sub_u32_e32 v131, v108, v239
	v_add_u32_e32 v132, 0x1750, v109
	v_add_u32_e32 v94, 0x1710, v109
	v_add_u32_e32 v95, 0x1748, v109
	ds_read2_b32 v[108:109], v94 offset1:1
	ds_read2_b32 v[110:111], v95 offset1:1
	ds_read2_b32 v[132:133], v132 offset1:1
	s_waitcnt lgkmcnt(3)
	v_fmamk_f32 v88, v90, 0x3e38aa3b, v88
	v_cmp_le_u32_e32 vcc, v131, v240
	v_fmac_f32_e32 v89, 0x3e38aa3b, v91
	s_waitcnt lgkmcnt(2)
	v_fmamk_f32 v92, v92, 0x3e38aa3b, v108
	v_cndmask_b32_e32 v90, v235, v88, vcc
	v_add_u32_e32 v88, 1, v131
	v_cmp_le_u32_e32 vcc, v88, v240
	v_add_u32_e32 v88, 2, v131
	v_fmac_f32_e32 v109, 0x3e38aa3b, v93
	v_cndmask_b32_e32 v89, v235, v89, vcc
	v_cmp_le_u32_e32 vcc, v88, v240
	v_add_u32_e32 v108, 3, v131
	v_max3_f32 v91, v90, s95, v89
	v_cndmask_b32_e32 v88, v235, v92, vcc
	v_mfma_f32_16x16x32_bf16 v[92:95], v[84:87], v[4:7], 0
	v_cmp_le_u32_e32 vcc, v108, v240
	v_mfma_f32_16x16x32_bf16 v[92:95], v[80:83], v[0:3], v[92:95]
	v_add_u32_e32 v80, 16, v131
	v_cndmask_b32_e32 v84, v235, v109, vcc
	v_cmp_le_u32_e32 vcc, v80, v240
	v_add_u32_e32 v80, 17, v131
	v_max3_f32 v85, v91, v88, v84
	s_waitcnt lgkmcnt(1)
	s_nop 1
	v_fmamk_f32 v81, v92, 0x3e38aa3b, v110
	v_cndmask_b32_e32 v83, v235, v81, vcc
	v_fmac_f32_e32 v111, 0x3e38aa3b, v93
	v_cmp_le_u32_e32 vcc, v80, v240
	v_add_u32_e32 v80, 18, v131
	s_waitcnt lgkmcnt(0)
	v_fmamk_f32 v81, v94, 0x3e38aa3b, v132
	v_cndmask_b32_e32 v82, v235, v111, vcc
	v_cmp_le_u32_e32 vcc, v80, v240
	v_add_u32_e32 v80, 19, v131
	v_fmac_f32_e32 v133, 0x3e38aa3b, v95
	v_cndmask_b32_e32 v81, v235, v81, vcc
	v_cmp_le_u32_e32 vcc, v80, v240
	v_max3_f32 v85, v85, v83, v82
	s_nop 0
	v_cndmask_b32_e32 v80, v235, v133, vcc
	v_max3_f32 v85, v85, v81, v80
	v_sub_f32_e32 v86, v85, v191
	v_cmp_lt_f32_e32 vcc, s19, v86
	s_cbranch_vccz .LBB0_589
	ds_bpermute_b32 v86, v207, v85
	v_max_f32_e32 v85, v85, v85
	s_waitcnt lgkmcnt(0)
	v_max_f32_e32 v86, v86, v86
	v_max_f32_e32 v85, v85, v86
	ds_bpermute_b32 v86, v206, v85
	s_waitcnt lgkmcnt(0)
	v_max3_f32 v85, v191, v85, v86
	v_sub_f32_e32 v86, v191, v85
	v_exp_f32_e32 v86, v86
	v_mov_b32_e32 v191, v85
	v_mul_f32_e32 v189, v189, v86
	v_pk_mul_f32 v[26:27], v[26:27], v[86:87] op_sel_hi:[1,0]
	v_pk_mul_f32 v[24:25], v[24:25], v[86:87] op_sel_hi:[1,0]
	v_pk_mul_f32 v[22:23], v[22:23], v[86:87] op_sel_hi:[1,0]
	v_pk_mul_f32 v[20:21], v[20:21], v[86:87] op_sel_hi:[1,0]
	v_pk_mul_f32 v[30:31], v[30:31], v[86:87] op_sel_hi:[1,0]
	v_pk_mul_f32 v[28:29], v[28:29], v[86:87] op_sel_hi:[1,0]
	v_pk_mul_f32 v[16:17], v[16:17], v[86:87] op_sel_hi:[1,0]
	v_pk_mul_f32 v[18:19], v[18:19], v[86:87] op_sel_hi:[1,0]
; #define LAS __attribute__((address_space(3)))
; template <bool EDGE>
; __device__ __forceinline__ void tile_load(TileLd& L, const bf16_t* kp, const bf16_t* vp, int S, int pos0, int dil, int k0, int lane) {
;     asm volatile("" : "+s"(k0), "+s"(pos0));
;     const int i16 = lane & 15, quad = lane >> 4;
; #pragma unroll
;     for (int st = 0; st < 2; ++st) { int pos = pos0 + dil * (k0 + 16 * st + i16); if (EDGE) pos = min(max(pos, 0), S - 1);
;         const bf16_t* p = kp + (long)pos * NIN + quad * 8; L.k[st][0] = *(const bf16x8*)p; L.k[st][1] = *(const bf16x8*)(p + 32); }
; #pragma unroll
;     for (int i = 0; i < 4; ++i) { int pos = pos0 + dil * (k0 + 8 * i + (lane >> 3)); if (EDGE) pos = min(max(pos, 0), S - 1);
;         L.v[i] = *(const u32x4*)(vp + (long)pos * NIN + (lane & 7) * 8); }
; }
; template <int G, bool EDGE> ...
;     asm volatile("" : "+s"(k0));
;     const int quad = lane >> 4; const f32x4 z4 = {0.f, 0.f, 0.f, 0.f};
;     bf16x8 vf[4]; stage_v_regs(L.v, vimg, lane, vf);
;     constexpr float C2 = 0.125f * LOG2E, THR = 6.0f;
;     const int kb = k0 + 4 * quad;
; #pragma unroll
;     for (int g = 0; g < G; ++g) {
;         const LAS float* lutb = lut + (kb - ua[g] + R);
;         float sc[8]; float mx = -1e30f;
; #pragma unroll
;         for (int st = 0; st < 2; ++st) { f32x4 s = MFMA16(L.k[st][0], q[g][0], z4); s = MFMA16(L.k[st][1], q[g][1], s);
; #pragma unroll
;             for (int jj = 0; jj < 4; ++jj) { const int c = 16 * st + jj; const bool v = (unsigned)(kb - klo[g] + c) <= (unsigned)kspan[g];
;                 float x = s[jj] * C2 + lutb[g * lutstride + c]; x = v ? x : -1e30f; sc[4 * st + jj] = x; mx = fmaxf(mx, x); } }
;         if (__any(mx - m[g] > THR)) {
;             mx = fmaxf(mx, shx(mx, 16, lane)); mx = fmaxf(mx, shx(mx, 32, lane));
;             const float mn = fmaxf(m[g], mx), al = ex2(m[g] - mn); m[g] = mn; l[g] *= al;
; #pragma unroll
;             for (int nn = 0; nn < 4; ++nn) o[g][nn] = o[g][nn] * al;
;         }
;         const float mn = m[g]; float p[8], ps = 0.f;
; #pragma unroll
;         for (int e = 0; e < 8; ++e) { p[e] = ex2(sc[e] - mn); ps += p[e]; }
;         l[g] += ps;
;         const u32x4 pw = {pg8::cvt_pk_vis(p[0], p[1]), pg8::cvt_pk_vis(p[2], p[3]), pg8::cvt_pk_vis(p[4], p[5]), pg8::cvt_pk_vis(p[6], p[7])}; const bf16x8 pf = __builtin_bit_cast(bf16x8, pw);
; #pragma unroll
.LBB0_589:
	v_sub_f32_e32 v85, v90, v191
	v_exp_f32_e32 v85, v85
	v_sub_f32_e32 v87, v89, v191
	v_exp_f32_e32 v87, v87
	v_sub_f32_e32 v88, v88, v191
	v_exp_f32_e32 v88, v88
	v_sub_f32_e32 v84, v84, v191
	v_exp_f32_e32 v84, v84
	v_sub_f32_e32 v83, v83, v191
	v_add_f32_e32 v86, 0, v85
	v_exp_f32_e32 v83, v83
	v_sub_f32_e32 v82, v82, v191
	v_add_f32_e32 v86, v87, v86
	v_exp_f32_e32 v82, v82
	v_sub_f32_e32 v81, v81, v191
	v_add_f32_e32 v86, v88, v86
	v_exp_f32_e32 v89, v81
	v_add_f32_e32 v86, v84, v86
	v_add_f32_e32 v86, v83, v86
	v_add_f32_e32 v86, v82, v86
	v_sub_f32_e32 v80, v80, v191
	v_add_f32_e32 v81, v89, v86
	v_exp_f32_e32 v86, v80
	v_cvt_pk_bf16_f32 v82, v83, v82
	s_mov_b32 s34, s1
	s_mov_b32 s35, s42
	v_add_f32_e32 v80, v86, v81
	v_add_f32_e32 v131, v189, v80
	v_cvt_pk_bf16_f32 v80, v85, v87
	v_cvt_pk_bf16_f32 v81, v88, v84
	v_cvt_pk_bf16_f32 v83, v89, v86
	s_waitcnt vmcnt(7)
	v_mfma_f32_16x16x32_bf16 v[112:115], v[112:115], v[4:7], 0
	v_mfma_f32_16x16x32_bf16 v[20:23], v[12:15], v[80:83], v[20:23]
	v_mfma_f32_16x16x32_bf16 v[12:15], v[96:99], v[80:83], v[24:27]
	s_nop 2
	v_add_u32_e32 v24, s34, v199
	v_lshl_add_u32 v26, v24, 4, s35
	v_med3_i32 v24, v26, 0, s70
	v_mad_u64_u32 v[24:25], s[24:25], v24, s97, v[186:187]
	global_load_dwordx4 v[92:95], v[24:25], off offset:1536
	global_load_dwordx4 v[88:91], v[24:25], off offset:1600
	v_add_u32_e32 v24, 0x100, v26
	v_med3_i32 v24, v24, 0, s70
	v_mad_u64_u32 v[24:25], s[24:25], v24, s97, v[186:187]
	v_mfma_f32_16x16x32_bf16 v[28:31], v[104:107], v[80:83], v[28:31]
	v_mfma_f32_16x16x32_bf16 v[16:19], v[100:103], v[80:83], v[16:19]
	global_load_dwordx4 v[84:87], v[24:25], off offset:1536
	global_load_dwordx4 v[80:83], v[24:25], off offset:1600
	v_add_u32_e32 v24, s34, v200
	v_lshl_add_u32 v26, v24, 4, s35
	v_med3_i32 v24, v26, 0, s70
	v_mad_u64_u32 v[24:25], s[24:25], v24, s97, v[120:121]
	global_load_dwordx4 v[96:99], v[24:25], off offset:3072
	v_add_u32_e32 v24, 0x80, v26
	v_med3_i32 v24, v24, 0, s70
	v_mad_u64_u32 v[24:25], s[24:25], v24, s97, v[120:121]
	global_load_dwordx4 v[100:103], v[24:25], off offset:3072
	v_add_u32_e32 v24, 0x100, v26
	v_med3_i32 v24, v24, 0, s70
	v_mad_u64_u32 v[24:25], s[24:25], v24, s97, v[120:121]
	global_load_dwordx4 v[104:107], v[24:25], off offset:3072
	v_add_u32_e32 v24, 0x180, v26
	v_med3_i32 v24, v24, 0, s70
	v_mad_u64_u32 v[24:25], s[24:25], v24, s97, v[120:121]
	global_load_dwordx4 v[108:111], v[24:25], off offset:3072
	s_waitcnt vmcnt(11)
	ds_write_b128 v122, v[40:43]
	s_waitcnt vmcnt(10)
	ds_write_b128 v122, v[52:55] offset:1152
	s_waitcnt vmcnt(9)
	ds_write_b128 v122, v[56:59] offset:2304
	s_waitcnt vmcnt(8)
	ds_write_b128 v122, v[116:119] offset:3456
	v_add_u32_e32 v116, s7, v204
	v_sub_u32_e32 v117, v116, v199
	v_lshl_add_u32 v117, v117, 2, s31
	ds_read_b64_tr_b16 v[56:57], v211
	ds_read_b64_tr_b16 v[52:53], v211 offset:32
	ds_read_b64_tr_b16 v[58:59], v211 offset:2304
	ds_read_b64_tr_b16 v[54:55], v211 offset:2336
	ds_read_b64_tr_b16 v[24:25], v211 offset:64
	ds_read_b64_tr_b16 v[26:27], v211 offset:2368
	ds_read_b64_tr_b16 v[40:41], v211 offset:96
	ds_read_b64_tr_b16 v[42:43], v211 offset:2400
	v_add_u32_e32 v118, 0x1708, v117
	v_mfma_f32_16x16x32_bf16 v[112:115], v[60:63], v[0:3], v[112:115]
	ds_read2_b32 v[62:63], v118 offset1:1
	v_sub_u32_e32 v116, v116, v239
	v_cmp_le_u32_e32 vcc, v116, v240
	v_mfma_f32_16x16x32_bf16 v[44:47], v[44:47], v[4:7], 0
	v_mfma_f32_16x16x32_bf16 v[46:49], v[48:51], v[0:3], v[44:47]
	s_waitcnt lgkmcnt(0)
	s_nop 1
	v_fmamk_f32 v60, v112, 0x3e38aa3b, v62
	v_cndmask_b32_e32 v61, v235, v60, vcc
	v_add_u32_e32 v60, 1, v116
	v_fmac_f32_e32 v63, 0x3e38aa3b, v113
	v_cmp_le_u32_e32 vcc, v60, v240
	v_add_u32_e32 v45, 0x1748, v117
	ds_read2_b32 v[50:51], v45 offset1:1
	v_cndmask_b32_e32 v60, v235, v63, vcc
	v_add_u32_e32 v63, 0x1710, v117
	ds_read2_b32 v[112:113], v63 offset1:1
	v_add_u32_e32 v62, 2, v116
	v_cmp_le_u32_e32 vcc, v62, v240
	v_add_u32_e32 v62, 3, v116
	v_add_u32_e32 v44, 16, v116
	s_waitcnt lgkmcnt(0)
	v_fmamk_f32 v63, v114, 0x3e38aa3b, v112
	v_cndmask_b32_e32 v63, v235, v63, vcc
	v_fmac_f32_e32 v113, 0x3e38aa3b, v115
	v_cmp_le_u32_e32 vcc, v62, v240
	v_fmamk_f32 v45, v46, 0x3e38aa3b, v50
	v_fmac_f32_e32 v51, 0x3e38aa3b, v47
	v_cndmask_b32_e32 v62, v235, v113, vcc
	v_cmp_le_u32_e32 vcc, v44, v240
	v_add_u32_e32 v44, 17, v116
	v_add_u32_e32 v47, 0x1750, v117
	v_cndmask_b32_e32 v45, v235, v45, vcc
	v_cmp_le_u32_e32 vcc, v44, v240
	v_add_u32_e32 v46, 18, v116
	v_max3_f32 v118, v61, s95, v60
	v_cndmask_b32_e32 v44, v235, v51, vcc
	ds_read2_b32 v[50:51], v47 offset1:1
	v_cmp_le_u32_e32 vcc, v46, v240
	v_add_u32_e32 v46, 19, v116
	v_max3_f32 v112, v118, v63, v62
	v_max3_f32 v112, v112, v45, v44
	s_waitcnt lgkmcnt(0)
	v_fmamk_f32 v47, v48, 0x3e38aa3b, v50
	v_cndmask_b32_e32 v47, v235, v47, vcc
	v_fmac_f32_e32 v51, 0x3e38aa3b, v49
	v_cmp_le_u32_e32 vcc, v46, v240
	s_nop 1
	v_cndmask_b32_e32 v46, v235, v51, vcc
	v_max3_f32 v48, v112, v47, v46
	v_sub_f32_e32 v49, v48, v191
	v_cmp_lt_f32_e32 vcc, s19, v49
	s_cbranch_vccz .LBB0_586
	ds_bpermute_b32 v49, v207, v48
	v_max_f32_e32 v48, v48, v48
	s_waitcnt lgkmcnt(0)
	v_max_f32_e32 v49, v49, v49
	v_max_f32_e32 v48, v48, v49
	ds_bpermute_b32 v49, v206, v48
	s_waitcnt lgkmcnt(0)
	v_max3_f32 v49, v191, v48, v49
	v_sub_f32_e32 v48, v191, v49
	v_exp_f32_e32 v48, v48
	v_mov_b32_e32 v191, v49
	v_mul_f32_e32 v131, v131, v48
	v_pk_mul_f32 v[30:31], v[30:31], v[48:49] op_sel_hi:[1,0]
	v_pk_mul_f32 v[28:29], v[28:29], v[48:49] op_sel_hi:[1,0]
	v_pk_mul_f32 v[22:23], v[22:23], v[48:49] op_sel_hi:[1,0]
	v_pk_mul_f32 v[20:21], v[20:21], v[48:49] op_sel_hi:[1,0]
	v_pk_mul_f32 v[14:15], v[14:15], v[48:49] op_sel_hi:[1,0]
	v_pk_mul_f32 v[12:13], v[12:13], v[48:49] op_sel_hi:[1,0]
	v_pk_mul_f32 v[18:19], v[18:19], v[48:49] op_sel_hi:[1,0]
	v_pk_mul_f32 v[16:17], v[16:17], v[48:49] op_sel_hi:[1,0]
	s_branch .LBB0_586

; #define LAS __attribute__((address_space(3)))
; #define C_STEP(CUR, NXT, TT, PF) do { if (PF) tile_load<EDGE>(NXT, kp, vp, S, P0, 1, -128 + 32 * ((TT) + 1), lane); \
;         attn_tile<3, EDGE>(CUR, klo_c, kspan_c, -128 + 32 * (TT), 128, ua_c, lut, 257, vimg, lane, q, o, m, l); } while (0)
; template <bool EDGE>
; __device__ __forceinline__ void tile_load(TileLd& L, const bf16_t* kp, const bf16_t* vp, int S, int pos0, int dil, int k0, int lane) {
;     asm volatile("" : "+s"(k0), "+s"(pos0));
;     const int i16 = lane & 15, quad = lane >> 4;
; #pragma unroll
;     for (int st = 0; st < 2; ++st) { int pos = pos0 + dil * (k0 + 16 * st + i16); if (EDGE) pos = min(max(pos, 0), S - 1);
;         const bf16_t* p = kp + (long)pos * NIN + quad * 8; L.k[st][0] = *(const bf16x8*)p; L.k[st][1] = *(const bf16x8*)(p + 32); }
; #pragma unroll
;     for (int i = 0; i < 4; ++i) { int pos = pos0 + dil * (k0 + 8 * i + (lane >> 3)); if (EDGE) pos = min(max(pos, 0), S - 1);
;         L.v[i] = *(const u32x4*)(vp + (long)pos * NIN + (lane & 7) * 8); }
; }
; template <bool EDGE>
; __device__ __forceinline__ void mixer_c_item(const bf16_t* kp, const bf16_t* vp, int S, int P0, const LAS float* lut, LAS unsigned char* vimg, int lane,
;                                              const bf16x8 (&q)[3][2], f32x4 (&o)[3][4], float (&m)[3], float (&l)[3]) {
;     const int i16 = lane & 15;
;     const int klo_1 = max(i16 - 128, -P0), kspan_1 = min(i16 + 128, S - 1 - P0) - klo_1; const int klo_c[3] = {klo_1, klo_1, klo_1}, kspan_c[3] = {kspan_1, kspan_1, kspan_1}, ua_c[3] = {i16, i16, i16};
;     TileLd ta, tb; tile_load<EDGE>(ta, kp, vp, S, P0, 1, -128, lane);
;     ...
; #pragma unroll 1
;     for (int t = 0; t < 8; t += 2) { C_STEP(ta, tb, t, true); C_STEP(tb, ta, t + 1, true); }
;     C_STEP(ta, tb, 8, false);
.LBB0_628:
	s_and_b64 vcc, exec, s[0:1]
	s_cbranch_vccz .LBB0_597
	s_mov_b32 s0, s52
	s_movk_i32 s1, 0xff80
	s_add_i32 s2, s0, s1
	v_add_u32_e32 v26, s2, v199
	v_lshl_add_u64 v[144:145], s[44:45], 0, v[156:157]
	v_med3_i32 v24, v26, 0, s70
	v_mad_u64_u32 v[24:25], s[0:1], v24, s97, v[144:145]
	global_load_dwordx4 v[36:39], v[24:25], off
	global_load_dwordx4 v[32:35], v[24:25], off offset:64
	v_add_u32_e32 v24, 16, v26
	v_add_u32_e32 v44, s2, v200
	v_mov_b32_e32 v143, v157
	v_add_u32_e32 v42, 8, v44
	v_med3_i32 v24, v24, 0, s70
	v_lshl_add_u64 v[142:143], s[24:25], 0, v[142:143]
	v_med3_i32 v40, v44, 0, s70
	v_mad_u64_u32 v[24:25], s[0:1], v24, s97, v[144:145]
	v_mad_u64_u32 v[40:41], s[0:1], v40, s97, v[142:143]
	v_med3_i32 v42, v42, 0, s70
	global_load_dwordx4 v[28:31], v[24:25], off
	s_nop 0
	global_load_dwordx4 v[24:27], v[24:25], off offset:64
	v_mad_u64_u32 v[42:43], s[0:1], v42, s97, v[142:143]
	global_load_dwordx4 v[104:107], v[40:41], off
	global_load_dwordx4 v[108:111], v[42:43], off
	v_add_u32_e32 v40, 16, v44
	v_add_u32_e32 v42, 24, v44
	v_med3_i32 v40, v40, 0, s70
	v_mad_u64_u32 v[40:41], s[0:1], v40, s97, v[142:143]
	v_med3_i32 v42, v42, 0, s70
	v_mad_u64_u32 v[42:43], s[0:1], v42, s97, v[142:143]
	global_load_dwordx4 v[112:115], v[40:41], off
	global_load_dwordx4 v[116:119], v[42:43], off
	s_sub_i32 s0, 0, s52
	v_max_i32_e32 v154, s0, v139
	s_not_b32 s0, s52
	v_readlane_b32 s1, v255, 21
	s_add_i32 s0, s1, s0
	v_min_i32_e32 v40, s0, v148
	v_mov_b32_e32 v42, v157
	v_mov_b32_e32 v43, v157
	v_sub_u32_e32 v152, v40, v154
	v_mov_b32_e32 v40, v157
	v_mov_b32_e32 v41, v157
	v_mov_b64_e32 v[46:47], v[42:43]
	v_mov_b64_e32 v[58:59], v[42:43]
	v_mov_b64_e32 v[62:63], v[42:43]
	v_mov_b64_e32 v[86:87], v[42:43]
	v_mov_b64_e32 v[82:83], v[42:43]
	v_mov_b64_e32 v[74:75], v[42:43]
	v_mov_b64_e32 v[78:79], v[42:43]
	v_mov_b64_e32 v[98:99], v[42:43]
	v_mov_b64_e32 v[90:91], v[42:43]
	v_mov_b64_e32 v[94:95], v[42:43]
	v_mov_b64_e32 v[102:103], v[42:43]
	v_mov_b32_e32 v151, 0
	s_mov_b32 s0, -2
	s_movk_i32 s1, 0xffc0
	v_mov_b64_e32 v[44:45], v[40:41]
	v_mov_b64_e32 v[56:57], v[40:41]
	v_mov_b64_e32 v[60:61], v[40:41]
	v_mov_b64_e32 v[84:85], v[40:41]
	v_mov_b64_e32 v[80:81], v[40:41]
	v_mov_b64_e32 v[72:73], v[40:41]
	v_mov_b64_e32 v[76:77], v[40:41]
	v_mov_b32_e32 v153, 0
	v_mov_b64_e32 v[96:97], v[40:41]
	v_mov_b64_e32 v[88:89], v[40:41]
	v_mov_b64_e32 v[92:93], v[40:41]
	v_mov_b64_e32 v[100:101], v[40:41]
	v_mov_b32_e32 v161, 0
	v_mov_b32_e32 v150, v136
	s_branch .LBB0_631

; template <bool EDGE>
; __device__ __forceinline__ void tile_load(TileLd& L, const bf16_t* kp, const bf16_t* vp, int S, int pos0, int dil, int k0, int lane) {
;     asm volatile("" : "+s"(k0), "+s"(pos0));
;     const int i16 = lane & 15, quad = lane >> 4;
; #pragma unroll
;     for (int st = 0; st < 2; ++st) { int pos = pos0 + dil * (k0 + 16 * st + i16); if (EDGE) pos = min(max(pos, 0), S - 1);
;         const bf16_t* p = kp + (long)pos * NIN + quad * 8; L.k[st][0] = *(const bf16x8*)p; L.k[st][1] = *(const bf16x8*)(p + 32); }
; #pragma unroll
;     for (int i = 0; i < 4; ++i) { int pos = pos0 + dil * (k0 + 8 * i + (lane >> 3)); if (EDGE) pos = min(max(pos, 0), S - 1);
;         L.v[i] = *(const u32x4*)(vp + (long)pos * NIN + (lane & 7) * 8); }
; }
; template <int G, bool EDGE> ...
;     asm volatile("" : "+s"(k0));
;     const int quad = lane >> 4; const f32x4 z4 = {0.f, 0.f, 0.f, 0.f};
;     bf16x8 vf[4]; stage_v_regs(L.v, vimg, lane, vf);
;     constexpr float C2 = 0.125f * LOG2E, THR = 6.0f;
;     const int kb = k0 + 4 * quad;
; #pragma unroll
;     for (int g = 0; g < G; ++g) {
;         const LAS float* lutb = lut + (kb - ua[g] + R);
;         float sc[8]; float mx = -1e30f;
; #pragma unroll
;         for (int st = 0; st < 2; ++st) { f32x4 s = MFMA16(L.k[st][0], q[g][0], z4); s = MFMA16(L.k[st][1], q[g][1], s);
; #pragma unroll
;             for (int jj = 0; jj < 4; ++jj) { const int c = 16 * st + jj; const bool v = (unsigned)(kb - klo[g] + c) <= (unsigned)kspan[g];
;                 float x = s[jj] * C2 + lutb[g * lutstride + c]; x = v ? x : -1e30f; sc[4 * st + jj] = x; mx = fmaxf(mx, x); } }
;         if (__any(mx - m[g] > THR)) {
;             mx = fmaxf(mx, shx(mx, 16, lane)); mx = fmaxf(mx, shx(mx, 32, lane));
;             const float mn = fmaxf(m[g], mx), al = ex2(m[g] - mn); m[g] = mn; l[g] *= al;
; #pragma unroll
;             for (int nn = 0; nn < 4; ++nn) o[g][nn] = o[g][nn] * al;
;         }
; template <bool EDGE>
; __device__ __forceinline__ void mixer_c_item(const bf16_t* kp, const bf16_t* vp, int S, int P0, const LAS float* lut, LAS unsigned char* vimg, int lane,
;                                              const bf16x8 (&q)[3][2], f32x4 (&o)[3][4], float (&m)[3], float (&l)[3]) {
;     ...
; #pragma unroll 1
;     for (int t = 0; t < 8; t += 2) { C_STEP(ta, tb, t, true); C_STEP(tb, ta, t + 1, true); }
.LBB0_631:
	s_sub_i32 s24, s1, 32
	s_mov_b32 s2, s52
	s_mov_b32 s3, s24
	s_add_i32 s4, s2, s3
	v_add_u32_e32 v50, s4, v199
	v_med3_i32 v48, v50, 0, s70
	v_mad_u64_u32 v[48:49], s[2:3], v48, s97, v[144:145]
	v_add_u32_e32 v132, s4, v200
	global_load_dwordx4 v[68:71], v[48:49], off
	global_load_dwordx4 v[64:67], v[48:49], off offset:64
	v_add_u32_e32 v48, 16, v50
	v_max_i32_e32 v120, 0, v132
	v_add_u32_e32 v124, 8, v132
	v_add_u32_e32 v128, 16, v132
	v_add_u32_e32 v132, 24, v132
	v_med3_i32 v48, v48, 0, s70
	v_min_i32_e32 v120, s70, v120
	v_med3_i32 v124, v124, 0, s70
	v_med3_i32 v128, v128, 0, s70
	v_med3_i32 v132, v132, 0, s70
	v_mad_u64_u32 v[52:53], s[2:3], v48, s97, v[144:145]
	v_mad_u64_u32 v[120:121], s[2:3], v120, s97, v[142:143]
	v_mad_u64_u32 v[124:125], s[2:3], v124, s97, v[142:143]
	v_mad_u64_u32 v[128:129], s[2:3], v128, s97, v[142:143]
	v_mad_u64_u32 v[132:133], s[2:3], v132, s97, v[142:143]
	global_load_dwordx4 v[48:51], v[52:53], off
	s_nop 0
	global_load_dwordx4 v[52:55], v[52:53], off offset:64
	s_sub_i32 s2, s1, 64
	global_load_dwordx4 v[120:123], v[120:121], off
	v_add_u32_e32 v155, v202, v203
	global_load_dwordx4 v[124:127], v[124:125], off
	s_waitcnt vmcnt(13)
	v_mfma_f32_16x16x32_bf16 v[170:173], v[36:39], v[16:19], 0
	global_load_dwordx4 v[128:131], v[128:129], off
	s_nop 0
	global_load_dwordx4 v[132:135], v[132:133], off
	s_waitcnt vmcnt(11)
	ds_write_b128 v155, v[104:107]
	s_waitcnt vmcnt(10)
	ds_write_b128 v155, v[108:111] offset:1152
	s_waitcnt vmcnt(9)
	ds_write_b128 v155, v[112:115] offset:2304
	s_waitcnt vmcnt(8)
	ds_write_b128 v155, v[116:119] offset:3456
	v_add_u32_e32 v162, s2, v204
	v_sub_u32_e32 v163, v162, v199
	v_lshl_add_u32 v167, v163, 2, s22
	ds_read_b64_tr_b16 v[116:117], v205
	ds_read_b64_tr_b16 v[104:105], v205 offset:32
	ds_read_b64_tr_b16 v[118:119], v205 offset:2304
	ds_read_b64_tr_b16 v[106:107], v205 offset:2336
	ds_read_b64_tr_b16 v[108:109], v205 offset:64
	ds_read_b64_tr_b16 v[110:111], v205 offset:2368
	ds_read_b64_tr_b16 v[112:113], v205 offset:96
	ds_read_b64_tr_b16 v[114:115], v205 offset:2400
	v_add_u32_e32 v163, 0x1400, v167
	v_sub_u32_e32 v178, v162, v154
	ds_read2_b32 v[162:163], v163 offset1:1
	v_mfma_f32_16x16x32_bf16 v[170:173], v[32:35], v[20:23], v[170:173]
	v_cmp_gt_u32_e64 s[2:3], v178, v152
	s_waitcnt lgkmcnt(0)
	s_nop 5
	v_fmamk_f32 v162, v170, 0x3e38aa3b, v162
	v_cndmask_b32_e64 v169, v162, v235, s[2:3]
	v_add_u32_e32 v162, 1, v178
	v_cmp_gt_u32_e64 s[4:5], v162, v152
	v_add_u32_e32 v162, 2, v178
	v_fmac_f32_e32 v163, 0x3e38aa3b, v171
	v_cmp_gt_u32_e64 s[6:7], v162, v152
	v_add_u32_e32 v162, 0x1408, v167
	v_cndmask_b32_e64 v170, v163, v235, s[4:5]
	ds_read2_b32 v[162:163], v162 offset1:1
	v_max3_f32 v174, v169, s95, v170
	s_waitcnt lgkmcnt(0)
	v_fmamk_f32 v162, v172, 0x3e38aa3b, v162
	v_cndmask_b32_e64 v171, v162, v235, s[6:7]
	v_add_u32_e32 v162, 3, v178
	v_cmp_gt_u32_e64 s[8:9], v162, v152
	v_fmac_f32_e32 v163, 0x3e38aa3b, v173
	v_add_u32_e32 v162, 16, v178
	v_cndmask_b32_e64 v172, v163, v235, s[8:9]
	v_max3_f32 v179, v174, v171, v172
	v_mfma_f32_16x16x32_bf16 v[174:177], v[28:31], v[16:19], 0
	v_cmp_gt_u32_e64 s[10:11], v162, v152
	v_add_u32_e32 v162, 0x1440, v167
	ds_read2_b32 v[162:163], v162 offset1:1
	v_mfma_f32_16x16x32_bf16 v[174:177], v[24:27], v[20:23], v[174:177]
	s_waitcnt lgkmcnt(0)
	s_nop 6
	v_fmamk_f32 v162, v174, 0x3e38aa3b, v162
	v_cndmask_b32_e64 v173, v162, v235, s[10:11]
	v_add_u32_e32 v162, 17, v178
	v_cmp_gt_u32_e64 s[12:13], v162, v152
	v_add_u32_e32 v162, 18, v178
	v_fmac_f32_e32 v163, 0x3e38aa3b, v175
	v_cmp_gt_u32_e64 s[14:15], v162, v152
	v_add_u32_e32 v162, 0x1448, v167
	v_cndmask_b32_e64 v174, v163, v235, s[12:13]
	ds_read2_b32 v[162:163], v162 offset1:1
	v_max3_f32 v179, v179, v173, v174
	s_waitcnt lgkmcnt(0)
	v_fmamk_f32 v162, v176, 0x3e38aa3b, v162
	v_cndmask_b32_e64 v175, v162, v235, s[14:15]
	v_add_u32_e32 v162, 19, v178
	v_cmp_gt_u32_e64 s[16:17], v162, v152
	v_fmac_f32_e32 v163, 0x3e38aa3b, v177
	s_nop 0
	v_cndmask_b32_e64 v176, v163, v235, s[16:17]
	v_max3_f32 v177, v179, v175, v176
	v_sub_f32_e32 v162, v177, v150
	v_cmp_lt_f32_e32 vcc, s19, v162
	s_cbranch_vccz .LBB0_633
	ds_bpermute_b32 v162, v207, v177
	v_max_f32_e32 v163, v177, v177
	s_waitcnt lgkmcnt(0)
	v_max_f32_e32 v162, v162, v162
	v_max_f32_e32 v162, v163, v162
	ds_bpermute_b32 v163, v206, v162
	s_waitcnt lgkmcnt(0)
	v_max3_f32 v162, v150, v162, v163
	v_sub_f32_e32 v150, v150, v162
	v_exp_f32_e32 v150, v150
	s_nop 0
	v_mul_f32_e32 v161, v161, v150
	v_pk_mul_f32 v[102:103], v[102:103], v[150:151] op_sel_hi:[1,0]
	v_pk_mul_f32 v[100:101], v[100:101], v[150:151] op_sel_hi:[1,0]
	v_pk_mul_f32 v[94:95], v[94:95], v[150:151] op_sel_hi:[1,0]
	v_pk_mul_f32 v[92:93], v[92:93], v[150:151] op_sel_hi:[1,0]
	v_pk_mul_f32 v[90:91], v[90:91], v[150:151] op_sel_hi:[1,0]
	v_pk_mul_f32 v[88:89], v[88:89], v[150:151] op_sel_hi:[1,0]
	v_pk_mul_f32 v[98:99], v[98:99], v[150:151] op_sel_hi:[1,0]
	v_pk_mul_f32 v[96:97], v[96:97], v[150:151] op_sel_hi:[1,0]
	v_mov_b32_e32 v150, v162

; #define LAS __attribute__((address_space(3)))
; template <bool EDGE>
; __device__ __forceinline__ void tile_load(TileLd& L, const bf16_t* kp, const bf16_t* vp, int S, int pos0, int dil, int k0, int lane) {
;     asm volatile("" : "+s"(k0), "+s"(pos0));
;     const int i16 = lane & 15, quad = lane >> 4;
; #pragma unroll
;     for (int st = 0; st < 2; ++st) { int pos = pos0 + dil * (k0 + 16 * st + i16); if (EDGE) pos = min(max(pos, 0), S - 1);
;         const bf16_t* p = kp + (long)pos * NIN + quad * 8; L.k[st][0] = *(const bf16x8*)p; L.k[st][1] = *(const bf16x8*)(p + 32); }
; #pragma unroll
;     for (int i = 0; i < 4; ++i) { int pos = pos0 + dil * (k0 + 8 * i + (lane >> 3)); if (EDGE) pos = min(max(pos, 0), S - 1);
;         L.v[i] = *(const u32x4*)(vp + (long)pos * NIN + (lane & 7) * 8); }
; }
; template <int G, bool EDGE> ...
;     asm volatile("" : "+s"(k0));
;     const int quad = lane >> 4; const f32x4 z4 = {0.f, 0.f, 0.f, 0.f};
;     bf16x8 vf[4]; stage_v_regs(L.v, vimg, lane, vf);
;     constexpr float C2 = 0.125f * LOG2E, THR = 6.0f;
;     const int kb = k0 + 4 * quad;
; #pragma unroll
;     for (int g = 0; g < G; ++g) {
;         const LAS float* lutb = lut + (kb - ua[g] + R);
;         float sc[8]; float mx = -1e30f;
; #pragma unroll
;         for (int st = 0; st < 2; ++st) { f32x4 s = MFMA16(L.k[st][0], q[g][0], z4); s = MFMA16(L.k[st][1], q[g][1], s);
; #pragma unroll
;             for (int jj = 0; jj < 4; ++jj) { const int c = 16 * st + jj; const bool v = (unsigned)(kb - klo[g] + c) <= (unsigned)kspan[g];
;                 float x = s[jj] * C2 + lutb[g * lutstride + c]; x = v ? x : -1e30f; sc[4 * st + jj] = x; mx = fmaxf(mx, x); } }
;         if (__any(mx - m[g] > THR)) {
;             mx = fmaxf(mx, shx(mx, 16, lane)); mx = fmaxf(mx, shx(mx, 32, lane));
;             const float mn = fmaxf(m[g], mx), al = ex2(m[g] - mn); m[g] = mn; l[g] *= al;
; #pragma unroll
;             for (int nn = 0; nn < 4; ++nn) o[g][nn] = o[g][nn] * al;
;         }
;         const float mn = m[g]; float p[8], ps = 0.f;
; #pragma unroll
;         for (int e = 0; e < 8; ++e) { p[e] = ex2(sc[e] - mn); ps += p[e]; }
;         l[g] += ps;
;         const u32x4 pw = {pg8::cvt_pk_vis(p[0], p[1]), pg8::cvt_pk_vis(p[2], p[3]), pg8::cvt_pk_vis(p[4], p[5]), pg8::cvt_pk_vis(p[6], p[7])}; const bf16x8 pf = __builtin_bit_cast(bf16x8, pw);
; #pragma unroll
.LBB0_637:
	v_add_f32_e32 v29, 0, v169
	v_add_f32_e32 v29, v170, v29
	v_add_f32_e32 v29, v171, v29
	v_add_f32_e32 v29, v172, v29
	v_add_f32_e32 v29, v173, v29
	v_add_f32_e32 v29, v174, v29
	v_add_f32_e32 v29, v175, v29
	v_add_f32_e32 v29, v176, v29
	v_sub_f32_e32 v24, v24, v138
	v_add_f32_e32 v161, v161, v29
	v_sub_f32_e32 v29, v32, v138
	v_exp_f32_e32 v173, v24
	v_sub_f32_e32 v24, v25, v138
	v_exp_f32_e32 v169, v29
	v_sub_f32_e32 v29, v33, v138
	v_exp_f32_e32 v174, v24
	v_sub_f32_e32 v24, v26, v138
	v_exp_f32_e32 v170, v29
	v_sub_f32_e32 v29, v34, v138
	v_sub_f32_e32 v28, v28, v138
	v_exp_f32_e32 v175, v24
	v_sub_f32_e32 v24, v27, v138
	v_exp_f32_e32 v171, v29
	v_exp_f32_e32 v172, v28
	v_exp_f32_e32 v176, v24
	s_mov_b32 s2, s1
	s_mov_b32 s3, s52
	v_cvt_pk_bf16_f32 v24, v169, v170
	v_cvt_pk_bf16_f32 v25, v171, v172
	v_cvt_pk_bf16_f32 v26, v173, v174
	v_cvt_pk_bf16_f32 v27, v175, v176
	s_add_i32 s4, s3, s2
	s_waitcnt vmcnt(7)
	v_mfma_f32_16x16x32_bf16 v[186:189], v[68:71], v[16:19], 0
	v_mfma_f32_16x16x32_bf16 v[60:63], v[116:119], v[24:27], v[60:63]
	v_add_u32_e32 v116, s4, v200
	v_mfma_f32_16x16x32_bf16 v[56:59], v[104:107], v[24:27], v[56:59]
	v_med3_i32 v104, v116, 0, s70
	v_mad_u64_u32 v[104:105], s[2:3], v104, s97, v[142:143]
	v_mfma_f32_16x16x32_bf16 v[44:47], v[108:111], v[24:27], v[44:47]
	v_add_u32_e32 v108, 8, v116
	v_med3_i32 v108, v108, 0, s70
	v_mfma_f32_16x16x32_bf16 v[40:43], v[112:115], v[24:27], v[40:43]
	v_add_u32_e32 v26, s4, v199
	v_med3_i32 v24, v26, 0, s70
	v_mad_u64_u32 v[24:25], s[2:3], v24, s97, v[144:145]
	global_load_dwordx4 v[36:39], v[24:25], off
	global_load_dwordx4 v[32:35], v[24:25], off offset:64
	v_add_u32_e32 v24, 16, v26
	v_add_u32_e32 v112, 16, v116
	v_add_u32_e32 v116, 24, v116
	v_med3_i32 v24, v24, 0, s70
	v_med3_i32 v112, v112, 0, s70
	v_med3_i32 v116, v116, 0, s70
	v_mad_u64_u32 v[24:25], s[2:3], v24, s97, v[144:145]
	v_mad_u64_u32 v[108:109], s[2:3], v108, s97, v[142:143]
	v_mad_u64_u32 v[112:113], s[2:3], v112, s97, v[142:143]
	v_mad_u64_u32 v[116:117], s[2:3], v116, s97, v[142:143]
	global_load_dwordx4 v[28:31], v[24:25], off
	s_nop 0
	global_load_dwordx4 v[24:27], v[24:25], off offset:64
	s_waitcnt vmcnt(10)
	v_mfma_f32_16x16x32_bf16 v[186:189], v[64:67], v[20:23], v[186:189]
	global_load_dwordx4 v[104:107], v[104:105], off
	s_nop 0
	global_load_dwordx4 v[108:111], v[108:109], off
	s_nop 0
	global_load_dwordx4 v[112:115], v[112:113], off
	s_nop 0
	global_load_dwordx4 v[116:119], v[116:117], off
	s_waitcnt vmcnt(11)
	ds_write_b128 v155, v[120:123]
	s_waitcnt vmcnt(10)
	ds_write_b128 v155, v[124:127] offset:1152
	s_waitcnt vmcnt(9)
	ds_write_b128 v155, v[128:131] offset:2304
	s_waitcnt vmcnt(8)
	ds_write_b128 v155, v[132:135] offset:3456
	v_add_u32_e32 v162, s24, v204
	v_sub_u32_e32 v163, v162, v199
	v_lshl_add_u32 v167, v163, 2, s22
	ds_read_b64_tr_b16 v[124:125], v205
	ds_read_b64_tr_b16 v[120:121], v205 offset:32
	ds_read_b64_tr_b16 v[126:127], v205 offset:2304
	ds_read_b64_tr_b16 v[122:123], v205 offset:2336
	ds_read_b64_tr_b16 v[132:133], v205 offset:64
	ds_read_b64_tr_b16 v[134:135], v205 offset:2368
	ds_read_b64_tr_b16 v[128:129], v205 offset:96
	ds_read_b64_tr_b16 v[130:131], v205 offset:2400
	v_add_u32_e32 v163, 0x1400, v167
	v_sub_u32_e32 v194, v162, v154
	ds_read2_b32 v[162:163], v163 offset1:1
	v_cmp_gt_u32_e64 s[8:9], v194, v152
	s_waitcnt lgkmcnt(0)
	v_fmamk_f32 v162, v186, 0x3e38aa3b, v162
	v_cndmask_b32_e64 v185, v162, v235, s[8:9]
	v_add_u32_e32 v162, 1, v194
	v_cmp_gt_u32_e64 s[10:11], v162, v152
	v_add_u32_e32 v162, 2, v194
	v_fmac_f32_e32 v163, 0x3e38aa3b, v187
	v_cmp_gt_u32_e64 s[4:5], v162, v152
	v_add_u32_e32 v162, 0x1408, v167
	v_cndmask_b32_e64 v186, v163, v235, s[10:11]
	ds_read2_b32 v[162:163], v162 offset1:1
	v_max3_f32 v190, v185, s95, v186
	s_waitcnt lgkmcnt(0)
	v_fmamk_f32 v162, v188, 0x3e38aa3b, v162
	v_cndmask_b32_e64 v187, v162, v235, s[4:5]
	v_add_u32_e32 v162, 3, v194
	v_cmp_gt_u32_e64 s[12:13], v162, v152
	v_fmac_f32_e32 v163, 0x3e38aa3b, v189
	v_add_u32_e32 v162, 16, v194
	v_cndmask_b32_e64 v188, v163, v235, s[12:13]
	v_max3_f32 v195, v190, v187, v188
	v_mfma_f32_16x16x32_bf16 v[190:193], v[48:51], v[16:19], 0
	v_cmp_gt_u32_e64 s[6:7], v162, v152
	v_add_u32_e32 v162, 0x1440, v167
	ds_read2_b32 v[162:163], v162 offset1:1
	v_mfma_f32_16x16x32_bf16 v[190:193], v[52:55], v[20:23], v[190:193]
	s_waitcnt lgkmcnt(0)
	s_nop 6
	v_fmamk_f32 v162, v190, 0x3e38aa3b, v162
	v_cndmask_b32_e64 v189, v162, v235, s[6:7]
	v_add_u32_e32 v162, 17, v194
	v_cmp_gt_u32_e64 s[14:15], v162, v152
	v_add_u32_e32 v162, 18, v194
	v_fmac_f32_e32 v163, 0x3e38aa3b, v191
	v_cmp_gt_u32_e64 s[2:3], v162, v152
	v_add_u32_e32 v162, 0x1448, v167
	v_cndmask_b32_e64 v190, v163, v235, s[14:15]
	ds_read2_b32 v[162:163], v162 offset1:1
	v_max3_f32 v195, v195, v189, v190
	s_waitcnt lgkmcnt(0)
	v_fmamk_f32 v162, v192, 0x3e38aa3b, v162
	v_cndmask_b32_e64 v191, v162, v235, s[2:3]
	v_add_u32_e32 v162, 19, v194
	v_cmp_gt_u32_e64 s[16:17], v162, v152
	v_fmac_f32_e32 v163, 0x3e38aa3b, v193
	s_nop 0
	v_cndmask_b32_e64 v192, v163, v235, s[16:17]
	v_max3_f32 v193, v195, v191, v192
	v_sub_f32_e32 v162, v193, v150
	v_cmp_lt_f32_e32 vcc, s19, v162
	s_cbranch_vccz .LBB0_639
	ds_bpermute_b32 v162, v207, v193
	v_max_f32_e32 v163, v193, v193
	s_waitcnt lgkmcnt(0)
	v_max_f32_e32 v162, v162, v162
	v_max_f32_e32 v162, v163, v162
	ds_bpermute_b32 v163, v206, v162
	s_waitcnt lgkmcnt(0)
	v_max3_f32 v162, v150, v162, v163
	v_sub_f32_e32 v150, v150, v162
	v_exp_f32_e32 v150, v150
	s_nop 0
	v_mul_f32_e32 v161, v161, v150
	v_pk_mul_f32 v[102:103], v[102:103], v[150:151] op_sel_hi:[1,0]
	v_pk_mul_f32 v[100:101], v[100:101], v[150:151] op_sel_hi:[1,0]
	v_pk_mul_f32 v[94:95], v[94:95], v[150:151] op_sel_hi:[1,0]
	v_pk_mul_f32 v[92:93], v[92:93], v[150:151] op_sel_hi:[1,0]
	v_pk_mul_f32 v[90:91], v[90:91], v[150:151] op_sel_hi:[1,0]
	v_pk_mul_f32 v[88:89], v[88:89], v[150:151] op_sel_hi:[1,0]
	v_pk_mul_f32 v[98:99], v[98:99], v[150:151] op_sel_hi:[1,0]
	v_pk_mul_f32 v[96:97], v[96:97], v[150:151] op_sel_hi:[1,0]
	v_mov_b32_e32 v150, v162
